# inproj and ffn1 epilogue stores widened: quarter-wave exchange (v_permlane16_swap) so each lane stores 16 contiguous bytes, half the store instructions
# speedup vs baseline: 1.0200x; 1.0123x over previous
; DI f32x4 mfma16(bf16x8 a, bf16x8 b, f32x4 c) { return __builtin_amdgcn_mfma_f32_16x16x32_bf16(a, b, c, 0, 0, 0); }
; template <int NI>
; DI void gemm_kloop(f32x4 (&acc)[4][NI], const bf16_t* __restrict__ A, int lda, const bf16_t* __restrict__ B, int ldb, int K, bf16_t* sA, bf16_t* sB) {
;     ...
;   for (int kt = 0; kt < nk; ++kt) {
;     __syncthreads();
; #pragma unroll
;     for (int i = 0; i < 4; ++i) { int c = tid + 256 * i, row = c >> 3, kc = (c & 7) * 8; *(bf16x8*)(sA + row * 72 + kc) = ra[i]; }
; #pragma unroll
;     for (int i = 0; i < NB; ++i) { int c = tid + 256 * i, row = c >> 3, kc = (c & 7) * 8; *(bf16x8*)(sB + row * 72 + kc) = rb[i]; }
;     __syncthreads();
;     if (kt + 1 < nk) {
;       const int k0 = (kt + 1) * 64;
; #pragma unroll
;       for (int i = 0; i < 4; ++i) { int c = tid + 256 * i, row = c >> 3, kc = (c & 7) * 8; ra[i] = *(const bf16x8*)(A + (size_t)row * lda + k0 + kc); }
; #pragma unroll
;       for (int i = 0; i < NB; ++i) { int c = tid + 256 * i, row = c >> 3, kc = (c & 7) * 8; rb[i] = *(const bf16x8*)(B + (size_t)row * ldb + k0 + kc); }
;     }
;     __builtin_amdgcn_s_setprio(1);
; #pragma unroll
;     for (int ks = 0; ks < 2; ++ks) {
;       bf16x8 af[4];
; #pragma unroll
;       for (int mi = 0; mi < 4; ++mi) af[mi] = *(const bf16x8*)(sA + (wr * 64 + mi * 16 + lr) * 72 + ks * 32 + lq * 8);
; #pragma unroll
;       for (int nh = 0; nh < NI / 4; ++nh) {
;         bf16x8 bfr[4];
; #pragma unroll
;         for (int ni = 0; ni < 4; ++ni) bfr[ni] = *(const bf16x8*)(sB + (wc * (NI * 16) + (nh * 4 + ni) * 16 + lr) * 72 + ks * 32 + lq * 8);
; #pragma unroll
;         for (int mi = 0; mi < 4; ++mi)
; #pragma unroll
;           for (int ni = 0; ni < 4; ++ni) acc[mi][nh * 4 + ni] = mfma16(bfr[ni], af[mi], acc[mi][nh * 4 + ni]);
;       }
;     }
;     __builtin_amdgcn_s_setprio(0);
;   }
.LBB0_108:
	s_barrier
	s_waitcnt vmcnt(0)
	ds_write_b128 v222, v[46:49]
	ds_write_b128 v223, v[42:45]
	ds_write_b128 v224, v[38:41]
	ds_write_b128 v225, v[34:37]
	ds_write_b128 v222, v[30:33] offset:18432
	ds_write_b128 v223, v[26:29] offset:18432
	ds_write_b128 v224, v[22:25] offset:18432
	ds_write_b128 v225, v[18:21] offset:18432
	ds_write_b128 v233, v[14:17] offset:18432
	ds_write_b128 v234, v[10:13] offset:18432
	ds_write_b128 v235, v[6:9] offset:18432
	ds_write_b128 v236, v[2:5] offset:18432
	v_lshl_add_u64 v[2:3], v[194:195], 0, s[28:29]
	v_lshl_add_u64 v[4:5], v[196:197], 0, s[28:29]
	s_waitcnt lgkmcnt(0)
	s_barrier
	ds_read_b128 v[178:181], v221
	ds_read_b128 v[182:185], v221 offset:2304
	ds_read_b128 v[186:189], v221 offset:4608
	ds_read_b128 v[190:193], v221 offset:6912
	ds_read_b128 v[228:231], v0 offset:18432
	ds_read_b128 v[238:241], v0 offset:20736
	ds_read_b128 v[242:245], v0 offset:23040
	ds_read_b128 v[246:249], v0 offset:25344
	global_load_dwordx4 v[46:49], v[2:3], off
	global_load_dwordx4 v[42:45], v[4:5], off
	v_lshl_add_u64 v[2:3], v[198:199], 0, s[28:29]
	v_lshl_add_u64 v[4:5], v[202:203], 0, s[28:29]
	global_load_dwordx4 v[38:41], v[2:3], off
	global_load_dwordx4 v[34:37], v[4:5], off
	v_lshl_add_u64 v[2:3], v[204:205], 0, s[28:29]
	v_lshl_add_u64 v[4:5], v[206:207], 0, s[28:29]
	global_load_dwordx4 v[30:33], v[2:3], off
	global_load_dwordx4 v[26:29], v[4:5], off
	v_lshl_add_u64 v[2:3], v[208:209], 0, s[28:29]
	v_lshl_add_u64 v[4:5], v[210:211], 0, s[28:29]
	global_load_dwordx4 v[22:25], v[2:3], off
	global_load_dwordx4 v[18:21], v[4:5], off
	v_lshl_add_u64 v[2:3], v[212:213], 0, s[28:29]
	v_lshl_add_u64 v[4:5], v[214:215], 0, s[28:29]
	global_load_dwordx4 v[14:17], v[2:3], off
	global_load_dwordx4 v[10:13], v[4:5], off
	v_lshl_add_u64 v[2:3], v[216:217], 0, s[28:29]
	v_lshl_add_u64 v[4:5], v[218:219], 0, s[28:29]
	global_load_dwordx4 v[6:9], v[2:3], off
	s_nop 0
	global_load_dwordx4 v[2:5], v[4:5], off
	s_setprio 1
	s_waitcnt lgkmcnt(3)
	v_mfma_f32_16x16x32_bf16 v[110:113], v[228:231], v[178:181], v[110:113]
	v_mfma_f32_16x16x32_bf16 v[94:97], v[228:231], v[182:185], v[94:97]
	v_mfma_f32_16x16x32_bf16 v[78:81], v[228:231], v[186:189], v[78:81]
	v_mfma_f32_16x16x32_bf16 v[62:65], v[228:231], v[190:193], v[62:65]
	ds_read_b128 v[228:231], v0 offset:27648
	s_waitcnt lgkmcnt(3)
	v_mfma_f32_16x16x32_bf16 v[106:109], v[238:241], v[178:181], v[106:109]
	v_mfma_f32_16x16x32_bf16 v[90:93], v[238:241], v[182:185], v[90:93]
	v_mfma_f32_16x16x32_bf16 v[74:77], v[238:241], v[186:189], v[74:77]
	v_mfma_f32_16x16x32_bf16 v[58:61], v[238:241], v[190:193], v[58:61]
	ds_read_b128 v[238:241], v0 offset:29952
	s_waitcnt lgkmcnt(3)
	v_mfma_f32_16x16x32_bf16 v[102:105], v[242:245], v[178:181], v[102:105]
	v_mfma_f32_16x16x32_bf16 v[86:89], v[242:245], v[182:185], v[86:89]
	v_mfma_f32_16x16x32_bf16 v[70:73], v[242:245], v[186:189], v[70:73]
	v_mfma_f32_16x16x32_bf16 v[54:57], v[242:245], v[190:193], v[54:57]
	ds_read_b128 v[242:245], v0 offset:32256
	s_waitcnt lgkmcnt(3)
	v_mfma_f32_16x16x32_bf16 v[98:101], v[246:249], v[178:181], v[98:101]
	v_mfma_f32_16x16x32_bf16 v[82:85], v[246:249], v[182:185], v[82:85]
	v_mfma_f32_16x16x32_bf16 v[66:69], v[246:249], v[186:189], v[66:69]
	v_mfma_f32_16x16x32_bf16 v[50:53], v[246:249], v[190:193], v[50:53]
	ds_read_b128 v[246:249], v0 offset:34560
	s_waitcnt lgkmcnt(3)
	v_mfma_f32_16x16x32_bf16 v[174:177], v[228:231], v[178:181], v[174:177]
	v_mfma_f32_16x16x32_bf16 v[158:161], v[228:231], v[182:185], v[158:161]
	v_mfma_f32_16x16x32_bf16 v[142:145], v[228:231], v[186:189], v[142:145]
	v_mfma_f32_16x16x32_bf16 v[126:129], v[228:231], v[190:193], v[126:129]
	ds_read_b128 v[228:231], v0 offset:18496
	s_waitcnt lgkmcnt(3)
	v_mfma_f32_16x16x32_bf16 v[170:173], v[238:241], v[178:181], v[170:173]
	v_mfma_f32_16x16x32_bf16 v[154:157], v[238:241], v[182:185], v[154:157]
	v_mfma_f32_16x16x32_bf16 v[138:141], v[238:241], v[186:189], v[138:141]
	v_mfma_f32_16x16x32_bf16 v[122:125], v[238:241], v[190:193], v[122:125]
	ds_read_b128 v[238:241], v0 offset:20800
	s_waitcnt lgkmcnt(3)
	v_mfma_f32_16x16x32_bf16 v[166:169], v[242:245], v[178:181], v[166:169]
	v_mfma_f32_16x16x32_bf16 v[150:153], v[242:245], v[182:185], v[150:153]
	v_mfma_f32_16x16x32_bf16 v[134:137], v[242:245], v[186:189], v[134:137]
	v_mfma_f32_16x16x32_bf16 v[118:121], v[242:245], v[190:193], v[118:121]
	ds_read_b128 v[242:245], v0 offset:23104
	s_waitcnt lgkmcnt(3)
	v_mfma_f32_16x16x32_bf16 v[162:165], v[246:249], v[178:181], v[162:165]
	ds_read_b128 v[178:181], v221 offset:6976
	v_mfma_f32_16x16x32_bf16 v[146:149], v[246:249], v[182:185], v[146:149]
	ds_read_b128 v[182:185], v221 offset:4672
	v_mfma_f32_16x16x32_bf16 v[130:133], v[246:249], v[186:189], v[130:133]
	ds_read_b128 v[186:189], v221 offset:2368
	v_mfma_f32_16x16x32_bf16 v[114:117], v[246:249], v[190:193], v[114:117]
	ds_read_b128 v[190:193], v221 offset:64
	ds_read_b128 v[246:249], v0 offset:25408
	s_waitcnt lgkmcnt(4)
	v_mfma_f32_16x16x32_bf16 v[62:65], v[228:231], v[178:181], v[62:65]
	s_waitcnt lgkmcnt(3)
	v_mfma_f32_16x16x32_bf16 v[78:81], v[228:231], v[182:185], v[78:81]
	s_waitcnt lgkmcnt(2)
	v_mfma_f32_16x16x32_bf16 v[94:97], v[228:231], v[186:189], v[94:97]
	s_waitcnt lgkmcnt(1)
	v_mfma_f32_16x16x32_bf16 v[110:113], v[228:231], v[190:193], v[110:113]
	ds_read_b128 v[228:231], v0 offset:27712
	v_mfma_f32_16x16x32_bf16 v[58:61], v[238:241], v[178:181], v[58:61]
	v_mfma_f32_16x16x32_bf16 v[74:77], v[238:241], v[182:185], v[74:77]
	v_mfma_f32_16x16x32_bf16 v[90:93], v[238:241], v[186:189], v[90:93]
	v_mfma_f32_16x16x32_bf16 v[106:109], v[238:241], v[190:193], v[106:109]
	ds_read_b128 v[238:241], v0 offset:30016
	v_mfma_f32_16x16x32_bf16 v[54:57], v[242:245], v[178:181], v[54:57]
	v_mfma_f32_16x16x32_bf16 v[70:73], v[242:245], v[182:185], v[70:73]
	v_mfma_f32_16x16x32_bf16 v[86:89], v[242:245], v[186:189], v[86:89]
	v_mfma_f32_16x16x32_bf16 v[102:105], v[242:245], v[190:193], v[102:105]
	ds_read_b128 v[242:245], v0 offset:32320
	s_waitcnt lgkmcnt(3)
; DI f32x4 mfma16(bf16x8 a, bf16x8 b, f32x4 c) { return __builtin_amdgcn_mfma_f32_16x16x32_bf16(a, b, c, 0, 0, 0); }
; template <int NI>
; DI void gemm_kloop(f32x4 (&acc)[4][NI], const bf16_t* __restrict__ A, int lda, const bf16_t* __restrict__ B, int ldb, int K, bf16_t* sA, bf16_t* sB) {
;     ...
;   for (int kt = 0; kt < nk; ++kt) {
;     __syncthreads();
; #pragma unroll
;     for (int i = 0; i < 4; ++i) { int c = tid + 256 * i, row = c >> 3, kc = (c & 7) * 8; *(bf16x8*)(sA + row * 72 + kc) = ra[i]; }
; #pragma unroll
;     for (int i = 0; i < NB; ++i) { int c = tid + 256 * i, row = c >> 3, kc = (c & 7) * 8; *(bf16x8*)(sB + row * 72 + kc) = rb[i]; }
;     __syncthreads();
;     if (kt + 1 < nk) {
;       const int k0 = (kt + 1) * 64;
; #pragma unroll
;       for (int i = 0; i < 4; ++i) { int c = tid + 256 * i, row = c >> 3, kc = (c & 7) * 8; ra[i] = *(const bf16x8*)(A + (size_t)row * lda + k0 + kc); }
; #pragma unroll
;       for (int i = 0; i < NB; ++i) { int c = tid + 256 * i, row = c >> 3, kc = (c & 7) * 8; rb[i] = *(const bf16x8*)(B + (size_t)row * ldb + k0 + kc); }
;     }
;     __builtin_amdgcn_s_setprio(1);
; #pragma unroll
;     for (int ks = 0; ks < 2; ++ks) {
;       bf16x8 af[4];
; #pragma unroll
;       for (int mi = 0; mi < 4; ++mi) af[mi] = *(const bf16x8*)(sA + (wr * 64 + mi * 16 + lr) * 72 + ks * 32 + lq * 8);
; #pragma unroll
;       for (int nh = 0; nh < NI / 4; ++nh) {
;         bf16x8 bfr[4];
; #pragma unroll
;         for (int ni = 0; ni < 4; ++ni) bfr[ni] = *(const bf16x8*)(sB + (wc * (NI * 16) + (nh * 4 + ni) * 16 + lr) * 72 + ks * 32 + lq * 8);
; #pragma unroll
;         for (int mi = 0; mi < 4; ++mi)
; #pragma unroll
;           for (int ni = 0; ni < 4; ++ni) acc[mi][nh * 4 + ni] = mfma16(bfr[ni], af[mi], acc[mi][nh * 4 + ni]);
;       }
;     }
;     __builtin_amdgcn_s_setprio(0);
;   }
	v_mfma_f32_16x16x32_bf16 v[50:53], v[246:249], v[178:181], v[50:53]
	v_mfma_f32_16x16x32_bf16 v[66:69], v[246:249], v[182:185], v[66:69]
	v_mfma_f32_16x16x32_bf16 v[82:85], v[246:249], v[186:189], v[82:85]
	v_mfma_f32_16x16x32_bf16 v[98:101], v[246:249], v[190:193], v[98:101]
	ds_read_b128 v[246:249], v0 offset:34624
	s_waitcnt lgkmcnt(3)
	v_mfma_f32_16x16x32_bf16 v[126:129], v[228:231], v[178:181], v[126:129]
	v_mfma_f32_16x16x32_bf16 v[142:145], v[228:231], v[182:185], v[142:145]
	v_mfma_f32_16x16x32_bf16 v[158:161], v[228:231], v[186:189], v[158:161]
	v_mfma_f32_16x16x32_bf16 v[174:177], v[228:231], v[190:193], v[174:177]
	s_waitcnt lgkmcnt(2)
	v_mfma_f32_16x16x32_bf16 v[122:125], v[238:241], v[178:181], v[122:125]
	v_mfma_f32_16x16x32_bf16 v[138:141], v[238:241], v[182:185], v[138:141]
	v_mfma_f32_16x16x32_bf16 v[154:157], v[238:241], v[186:189], v[154:157]
	v_mfma_f32_16x16x32_bf16 v[170:173], v[238:241], v[190:193], v[170:173]
	s_waitcnt lgkmcnt(1)
	v_mfma_f32_16x16x32_bf16 v[118:121], v[242:245], v[178:181], v[118:121]
	v_mfma_f32_16x16x32_bf16 v[134:137], v[242:245], v[182:185], v[134:137]
	v_mfma_f32_16x16x32_bf16 v[150:153], v[242:245], v[186:189], v[150:153]
	v_mfma_f32_16x16x32_bf16 v[166:169], v[242:245], v[190:193], v[166:169]
	s_waitcnt lgkmcnt(0)
	v_mfma_f32_16x16x32_bf16 v[114:117], v[246:249], v[178:181], v[114:117]
	v_mfma_f32_16x16x32_bf16 v[130:133], v[246:249], v[182:185], v[130:133]
	v_mfma_f32_16x16x32_bf16 v[146:149], v[246:249], v[186:189], v[146:149]
	v_mfma_f32_16x16x32_bf16 v[162:165], v[246:249], v[190:193], v[162:165]
	s_setprio 0
	s_add_u32 s28, s28, 0x80
	s_addc_u32 s29, s29, 0
	s_cmpk_lg_i32 s28, 0x780
	s_cbranch_scc1 .LBB0_108
	v_and_b32_e32 v248, 16, v227
	v_lshrrev_b32_e32 v249, 1, v248
	v_add_u32_e32 v248, v248, v249
	v_mov_b32_e32 v249, 0
	s_barrier
	s_waitcnt vmcnt(11)
	ds_write_b128 v222, v[46:49]
	s_waitcnt vmcnt(10)
	ds_write_b128 v223, v[42:45]
	s_waitcnt vmcnt(9)
	ds_write_b128 v224, v[38:41]
	s_waitcnt vmcnt(8)
	ds_write_b128 v225, v[34:37]
	s_waitcnt vmcnt(7)
	ds_write_b128 v222, v[30:33] offset:18432
	s_waitcnt vmcnt(6)
	ds_write_b128 v223, v[26:29] offset:18432
	s_waitcnt vmcnt(5)
	ds_write_b128 v224, v[22:25] offset:18432
	s_waitcnt vmcnt(4)
	ds_write_b128 v225, v[18:21] offset:18432
	s_waitcnt vmcnt(3)
	ds_write_b128 v233, v[14:17] offset:18432
	s_waitcnt vmcnt(2)
	ds_write_b128 v234, v[10:13] offset:18432
	s_waitcnt vmcnt(1)
	ds_write_b128 v235, v[6:9] offset:18432
	s_waitcnt vmcnt(0)
	ds_write_b128 v236, v[2:5] offset:18432
	s_waitcnt lgkmcnt(0)
	s_barrier
	s_setprio 1
	ds_read_b128 v[2:5], v221
	ds_read_b128 v[10:13], v221 offset:2304
	ds_read_b128 v[14:17], v221 offset:4608
	ds_read_b128 v[26:29], v221 offset:6912
	ds_read_b128 v[6:9], v0 offset:18432
	ds_read_b128 v[18:21], v0 offset:20736
	ds_read_b128 v[22:25], v0 offset:23040
	ds_read_b128 v[30:33], v0 offset:25344
	s_waitcnt lgkmcnt(3)
	v_mfma_f32_16x16x32_bf16 v[206:209], v[6:9], v[26:29], v[62:65]
	s_waitcnt lgkmcnt(0)
	v_mfma_f32_16x16x32_bf16 v[98:101], v[30:33], v[2:5], v[98:101]
	v_mfma_f32_16x16x32_bf16 v[182:185], v[30:33], v[10:13], v[82:85]
	v_mfma_f32_16x16x32_bf16 v[190:193], v[18:21], v[14:17], v[74:77]
	v_mfma_f32_16x16x32_bf16 v[202:205], v[30:33], v[14:17], v[66:69]
	v_mfma_f32_16x16x32_bf16 v[210:213], v[18:21], v[26:29], v[58:61]
	v_mfma_f32_16x16x32_bf16 v[222:225], v[30:33], v[26:29], v[50:53]
	ds_read_b128 v[30:33], v0 offset:27648
	s_nop 0
	ds_read_b128 v[58:61], v0 offset:29952
	ds_read_b128 v[62:65], v0 offset:32256
	ds_read_b128 v[74:77], v0 offset:34560
	v_mfma_f32_16x16x32_bf16 v[94:97], v[6:9], v[10:13], v[94:97]
	v_mfma_f32_16x16x32_bf16 v[178:181], v[18:21], v[10:13], v[90:93]
	v_mfma_f32_16x16x32_bf16 v[42:45], v[6:9], v[2:5], v[110:113]
	v_mfma_f32_16x16x32_bf16 v[46:49], v[18:21], v[2:5], v[106:109]
	v_mfma_f32_16x16x32_bf16 v[102:105], v[22:25], v[2:5], v[102:105]
	v_mfma_f32_16x16x32_bf16 v[86:89], v[22:25], v[10:13], v[86:89]
	v_mfma_f32_16x16x32_bf16 v[186:189], v[6:9], v[14:17], v[78:81]
	v_mfma_f32_16x16x32_bf16 v[194:197], v[22:25], v[14:17], v[70:73]
	v_mfma_f32_16x16x32_bf16 v[214:217], v[22:25], v[26:29], v[54:57]
	s_waitcnt lgkmcnt(3)
	v_mfma_f32_16x16x32_bf16 v[70:73], v[30:33], v[2:5], v[174:177]
	s_waitcnt lgkmcnt(2)
	v_mfma_f32_16x16x32_bf16 v[66:69], v[58:61], v[2:5], v[170:173]
	s_waitcnt lgkmcnt(1)
	v_mfma_f32_16x16x32_bf16 v[50:53], v[62:65], v[2:5], v[166:169]
	s_waitcnt lgkmcnt(0)
	v_mfma_f32_16x16x32_bf16 v[2:5], v[74:77], v[2:5], v[162:165]
	v_mfma_f32_16x16x32_bf16 v[6:9], v[30:33], v[10:13], v[158:161]
	v_mfma_f32_16x16x32_bf16 v[18:21], v[58:61], v[10:13], v[154:157]
	v_mfma_f32_16x16x32_bf16 v[22:25], v[62:65], v[10:13], v[150:153]
	v_mfma_f32_16x16x32_bf16 v[34:37], v[74:77], v[10:13], v[146:149]
	v_mfma_f32_16x16x32_bf16 v[38:41], v[30:33], v[14:17], v[142:145]
	v_mfma_f32_16x16x32_bf16 v[54:57], v[58:61], v[14:17], v[138:141]
	v_mfma_f32_16x16x32_bf16 v[134:137], v[62:65], v[14:17], v[134:137]
	v_mfma_f32_16x16x32_bf16 v[130:133], v[74:77], v[14:17], v[130:133]
	v_mfma_f32_16x16x32_bf16 v[146:149], v[62:65], v[26:29], v[118:121]
	v_mfma_f32_16x16x32_bf16 v[150:153], v[74:77], v[26:29], v[114:117]
	ds_read_b128 v[82:85], v221 offset:64
	ds_read_b128 v[162:165], v221 offset:2368
	ds_read_b128 v[158:161], v221 offset:4672
	ds_read_b128 v[154:157], v221 offset:6976
	ds_read_b128 v[10:13], v0 offset:18496
	ds_read_b128 v[14:17], v0 offset:20800
	ds_read_b128 v[114:117], v0 offset:23104
	ds_read_b128 v[118:121], v0 offset:25408
	s_waitcnt lgkmcnt(3)
	v_mfma_f32_16x16x32_bf16 v[90:93], v[10:13], v[162:165], v[94:97]
	s_waitcnt lgkmcnt(2)
; DI int otid() { int t = (int)__builtin_amdgcn_workitem_id_x(); asm volatile("" : "+v"(t)); return t; }
; DI f32x4 mfma16(bf16x8 a, bf16x8 b, f32x4 c) { return __builtin_amdgcn_mfma_f32_16x16x32_bf16(a, b, c, 0, 0, 0); }
; DI float siluf_(float x) { return x / (1.f + __expf(-x)); }
; DI void st_bf4(bf16_t* dst, f32x4 v) { u32x2 o; o.x = pk2(v[0], v[1]); o.y = pk2(v[2], v[3]); *(u32x2*)dst = o; }
; template <int NI>
; DI void gemm_kloop(f32x4 (&acc)[4][NI], const bf16_t* __restrict__ A, int lda, const bf16_t* __restrict__ B, int ldb, int K, bf16_t* sA, bf16_t* sB) {
;     ...
;         for (int ni = 0; ni < 4; ++ni) bfr[ni] = *(const bf16x8*)(sB + (wc * (NI * 16) + (nh * 4 + ni) * 16 + lr) * 72 + ks * 32 + lq * 8);
; #pragma unroll
;         for (int mi = 0; mi < 4; ++mi)
; #pragma unroll
;           for (int ni = 0; ni < 4; ++ni) acc[mi][nh * 4 + ni] = mfma16(bfr[ni], af[mi], acc[mi][nh * 4 + ni]);
; DI void ffn1_item(const Params& p, int l, int item, bf16_t* lds) {
;     ...
;   const int lane = otid() & 63, wid = otid() >> 6;
; #pragma unroll
;   for (int mi = 0; mi < 4; ++mi)
; #pragma unroll
;     for (int np = 0; np < 4; ++np) {
;       const int t = m0 + (wid >> 1) * 64 + mi * 16 + (lane & 15);
;       const int hcol = (((n0 + (wid & 1) * 128) >> 5) + np) * 16 + (lane >> 4) * 4;
;       f32x4 g = acc[mi][np * 2], u = acc[mi][np * 2 + 1], o;
; #pragma unroll
;       for (int r = 0; r < 4; ++r) o[r] = siluf_(g[r]) * u[r];
;       st_bf4(hid + (size_t)t * FH + hcol, o);
	v_mfma_f32_16x16x32_bf16 v[94:97], v[14:17], v[162:165], v[178:181]
	ds_read_b128 v[166:169], v0 offset:27712
	ds_read_b128 v[170:173], v0 offset:30016
	ds_read_b128 v[174:177], v0 offset:32320
	ds_read_b128 v[178:181], v0 offset:34624
	v_mfma_f32_16x16x32_bf16 v[138:141], v[30:33], v[26:29], v[126:129]
	v_mfma_f32_16x16x32_bf16 v[142:145], v[58:61], v[26:29], v[122:125]
	v_mfma_f32_16x16x32_bf16 v[126:129], v[10:13], v[82:85], v[42:45]
	v_mfma_f32_16x16x32_bf16 v[122:125], v[14:17], v[82:85], v[46:49]
	s_waitcnt lgkmcnt(5)
	v_mfma_f32_16x16x32_bf16 v[106:109], v[114:117], v[82:85], v[102:105]
	s_waitcnt lgkmcnt(4)
	v_mfma_f32_16x16x32_bf16 v[110:113], v[118:121], v[82:85], v[98:101]
	v_mfma_f32_16x16x32_bf16 v[74:77], v[114:117], v[162:165], v[86:89]
	v_mfma_f32_16x16x32_bf16 v[78:81], v[118:121], v[162:165], v[182:185]
	v_mfma_f32_16x16x32_bf16 v[58:61], v[10:13], v[158:161], v[186:189]
	v_mfma_f32_16x16x32_bf16 v[62:65], v[14:17], v[158:161], v[190:193]
	v_mfma_f32_16x16x32_bf16 v[42:45], v[114:117], v[158:161], v[194:197]
	v_mfma_f32_16x16x32_bf16 v[46:49], v[118:121], v[158:161], v[202:205]
	v_mfma_f32_16x16x32_bf16 v[26:29], v[10:13], v[154:157], v[206:209]
	v_mfma_f32_16x16x32_bf16 v[30:33], v[14:17], v[154:157], v[210:213]
	v_mfma_f32_16x16x32_bf16 v[10:13], v[114:117], v[154:157], v[214:217]
	v_mfma_f32_16x16x32_bf16 v[14:17], v[118:121], v[154:157], v[222:225]
	s_waitcnt lgkmcnt(3)
	v_mfma_f32_16x16x32_bf16 v[114:117], v[166:169], v[82:85], v[70:73]
	s_waitcnt lgkmcnt(2)
	v_mfma_f32_16x16x32_bf16 v[118:121], v[170:173], v[82:85], v[66:69]
	s_waitcnt lgkmcnt(1)
	v_mfma_f32_16x16x32_bf16 v[102:105], v[174:177], v[82:85], v[50:53]
	s_waitcnt lgkmcnt(0)
	v_mfma_f32_16x16x32_bf16 v[98:101], v[178:181], v[82:85], v[2:5]
	v_mfma_f32_16x16x32_bf16 v[82:85], v[166:169], v[162:165], v[6:9]
	v_mfma_f32_16x16x32_bf16 v[86:89], v[170:173], v[162:165], v[18:21]
	v_mfma_f32_16x16x32_bf16 v[70:73], v[174:177], v[162:165], v[22:25]
	v_mfma_f32_16x16x32_bf16 v[66:69], v[178:181], v[162:165], v[34:37]
	v_mfma_f32_16x16x32_bf16 v[50:53], v[166:169], v[158:161], v[38:41]
	v_mfma_f32_16x16x32_bf16 v[54:57], v[170:173], v[158:161], v[54:57]
	v_mfma_f32_16x16x32_bf16 v[38:41], v[174:177], v[158:161], v[134:137]
	v_mfma_f32_16x16x32_bf16 v[34:37], v[178:181], v[158:161], v[130:133]
	v_mfma_f32_16x16x32_bf16 v[18:21], v[166:169], v[154:157], v[138:141]
	v_mfma_f32_16x16x32_bf16 v[22:25], v[170:173], v[154:157], v[142:145]
	v_mfma_f32_16x16x32_bf16 v[6:9], v[174:177], v[154:157], v[146:149]
	v_mfma_f32_16x16x32_bf16 v[2:5], v[178:181], v[154:157], v[150:153]
	s_setprio 0
	v_mov_b32_e32 v130, v201
	v_mov_b32_e32 v131, v201
	v_mul_f32_e32 v135, 0xbfb8aa3b, v127
	v_ashrrev_i32_e32 v0, 1, v131
	v_lshlrev_b32_e32 v131, 1, v131
	v_and_b32_e32 v131, 0x80, v131
	v_or_b32_e32 v134, s24, v131
	v_ashrrev_i32_e32 v137, 1, v134
	v_mul_f32_e32 v134, 0xbfb8aa3b, v126
	v_exp_f32_e32 v134, v134
	v_exp_f32_e32 v135, v135
	v_and_b32_e32 v0, 0xffffffc0, v0
	v_lshrrev_b32_e32 v136, 2, v130
	v_add_u32_e32 v0, s26, v0
	v_pk_add_f32 v[134:135], v[134:135], 1.0 op_sel_hi:[1,0]
	v_and_or_b32 v0, v130, 15, v0
	v_div_scale_f32 v138, s[10:11], v135, v135, v127
	v_rcp_f32_e32 v139, v138
	v_mov_b64_e32 v[130:131], s[2:3]
	s_movk_i32 s12, 0x1600
	v_mad_i64_i32 v[132:133], s[10:11], v0, s12, v[130:131]
	v_fma_f32 v140, -v138, v139, 1.0
	v_fmac_f32_e32 v139, v140, v139
	v_div_scale_f32 v140, vcc, v127, v135, v127
	v_mul_f32_e32 v141, v140, v139
	v_fma_f32 v142, -v138, v141, v140
	v_fmac_f32_e32 v141, v142, v139
	v_fma_f32 v138, -v138, v141, v140
	v_div_fmas_f32 v138, v138, v139, v141
	v_div_fixup_f32 v127, v138, v135, v127
	v_div_scale_f32 v135, s[10:11], v134, v134, v126
	v_rcp_f32_e32 v138, v135
	s_add_i32 s9, s9, s4
	s_cmpk_gt_i32 s9, 0x15f
	v_fma_f32 v139, -v135, v138, 1.0
	v_fmac_f32_e32 v138, v139, v138
	v_div_scale_f32 v139, vcc, v126, v134, v126
	v_mul_f32_e32 v140, v139, v138
	v_fma_f32 v141, -v135, v140, v139
	v_fmac_f32_e32 v140, v141, v138
	v_fma_f32 v135, -v135, v140, v139
	v_div_fmas_f32 v135, v135, v138, v140
	v_div_fixup_f32 v126, v135, v134, v126
	v_pk_mul_f32 v[126:127], v[122:123], v[126:127]
	v_mul_f32_e32 v122, 0xbfb8aa3b, v128
	v_mul_f32_e32 v123, 0xbfb8aa3b, v129
	v_exp_f32_e32 v122, v122
	v_exp_f32_e32 v123, v123
	v_cvt_pk_bf16_f32 v126, v126, v127
	v_pk_add_f32 v[122:123], v[122:123], 1.0 op_sel_hi:[1,0]
	s_nop 0
	v_div_scale_f32 v134, s[10:11], v123, v123, v129
	v_rcp_f32_e32 v135, v134
	s_nop 0
	v_fma_f32 v138, -v134, v135, 1.0
	v_fmac_f32_e32 v135, v138, v135
	v_div_scale_f32 v138, vcc, v129, v123, v129
	v_mul_f32_e32 v139, v138, v135
	v_fma_f32 v140, -v134, v139, v138
	v_fmac_f32_e32 v139, v140, v135
	v_fma_f32 v134, -v134, v139, v138
	v_div_fmas_f32 v134, v134, v135, v139
	v_div_fixup_f32 v123, v134, v123, v129
	v_div_scale_f32 v129, s[10:11], v122, v122, v128
	v_rcp_f32_e32 v134, v129
	s_nop 0
	v_fma_f32 v135, -v129, v134, 1.0
	v_fmac_f32_e32 v134, v135, v134
	v_div_scale_f32 v135, vcc, v128, v122, v128
	v_mul_f32_e32 v138, v135, v134
	v_fma_f32 v139, -v129, v138, v135
	v_fmac_f32_e32 v138, v139, v134
	v_fma_f32 v129, -v129, v138, v135
	v_div_fmas_f32 v129, v129, v134, v138
	v_div_fixup_f32 v122, v129, v122, v128
	v_pk_mul_f32 v[128:129], v[124:125], v[122:123]
	v_and_or_b32 v122, v136, 12, v137
	v_ashrrev_i32_e32 v123, 31, v122
	v_lshlrev_b64 v[122:123], 1, v[122:123]
	v_lshl_add_u64 v[124:125], v[132:133], 0, v[122:123]
	v_cvt_pk_bf16_f32 v127, v128, v129
	v_mov_b32_e32 v238, v126
	v_mov_b32_e32 v239, v127
	v_mul_f32_e32 v126, 0xbfb8aa3b, v106
	v_mul_f32_e32 v127, 0xbfb8aa3b, v107
	v_exp_f32_e32 v126, v126
	v_exp_f32_e32 v127, v127
	s_nop 0
; DI float siluf_(float x) { return x / (1.f + __expf(-x)); }
; DI void st_bf4(bf16_t* dst, f32x4 v) { u32x2 o; o.x = pk2(v[0], v[1]); o.y = pk2(v[2], v[3]); *(u32x2*)dst = o; }
; DI void ffn1_item(const Params& p, int l, int item, bf16_t* lds) {
;     ...
;     for (int np = 0; np < 4; ++np) {
;       const int t = m0 + (wid >> 1) * 64 + mi * 16 + (lane & 15);
;       const int hcol = (((n0 + (wid & 1) * 128) >> 5) + np) * 16 + (lane >> 4) * 4;
;       f32x4 g = acc[mi][np * 2], u = acc[mi][np * 2 + 1], o;
; #pragma unroll
;       for (int r = 0; r < 4; ++r) o[r] = siluf_(g[r]) * u[r];
;       st_bf4(hid + (size_t)t * FH + hcol, o);
	v_pk_add_f32 v[126:127], v[126:127], 1.0 op_sel_hi:[1,0]
	s_nop 0
	v_div_scale_f32 v128, s[10:11], v127, v127, v107
	v_rcp_f32_e32 v129, v128
	s_nop 0
	v_fma_f32 v132, -v128, v129, 1.0
	v_fmac_f32_e32 v129, v132, v129
	v_div_scale_f32 v132, vcc, v107, v127, v107
	v_mul_f32_e32 v133, v132, v129
	v_fma_f32 v134, -v128, v133, v132
	v_fmac_f32_e32 v133, v134, v129
	v_fma_f32 v128, -v128, v133, v132
	v_div_fmas_f32 v128, v128, v129, v133
	v_div_fixup_f32 v107, v128, v127, v107
	v_div_scale_f32 v127, s[10:11], v126, v126, v106
	v_rcp_f32_e32 v128, v127
	s_nop 0
	v_fma_f32 v129, -v127, v128, 1.0
	v_fmac_f32_e32 v128, v129, v128
	v_div_scale_f32 v129, vcc, v106, v126, v106
	v_mul_f32_e32 v132, v129, v128
	v_fma_f32 v133, -v127, v132, v129
	v_fmac_f32_e32 v132, v133, v128
	v_fma_f32 v127, -v127, v132, v129
	v_div_fmas_f32 v127, v127, v128, v132
	v_div_fixup_f32 v106, v127, v126, v106
	v_pk_mul_f32 v[106:107], v[110:111], v[106:107]
	v_mul_f32_e32 v110, 0xbfb8aa3b, v108
	v_mul_f32_e32 v111, 0xbfb8aa3b, v109
	v_exp_f32_e32 v110, v110
	v_exp_f32_e32 v111, v111
	v_cvt_pk_bf16_f32 v106, v106, v107
	v_pk_add_f32 v[110:111], v[110:111], 1.0 op_sel_hi:[1,0]
	s_nop 0
	v_div_scale_f32 v126, s[10:11], v111, v111, v109
	v_rcp_f32_e32 v127, v126
	s_nop 0
	v_fma_f32 v128, -v126, v127, 1.0
	v_fmac_f32_e32 v127, v128, v127
	v_div_scale_f32 v128, vcc, v109, v111, v109
	v_mul_f32_e32 v129, v128, v127
	v_fma_f32 v132, -v126, v129, v128
	v_fmac_f32_e32 v129, v132, v127
	v_fma_f32 v126, -v126, v129, v128
	v_div_fmas_f32 v126, v126, v127, v129
	v_div_fixup_f32 v109, v126, v111, v109
	v_div_scale_f32 v111, s[10:11], v110, v110, v108
	v_rcp_f32_e32 v126, v111
	s_nop 0
	v_fma_f32 v127, -v111, v126, 1.0
	v_fmac_f32_e32 v126, v127, v126
	v_div_scale_f32 v127, vcc, v108, v110, v108
	v_mul_f32_e32 v128, v127, v126
	v_fma_f32 v129, -v111, v128, v127
	v_fmac_f32_e32 v128, v129, v126
	v_fma_f32 v111, -v111, v128, v127
	v_div_fmas_f32 v111, v111, v126, v128
	v_div_fixup_f32 v108, v111, v110, v108
	v_pk_mul_f32 v[108:109], v[112:113], v[108:109]
	s_nop 0
	v_cvt_pk_bf16_f32 v107, v108, v109
	v_mov_b32_e32 v240, v106
	v_mov_b32_e32 v241, v107
	v_lshl_add_u64 v[246:247], v[124:125], 0, v[248:249]
	s_nop 0
	v_permlane16_swap_b32_e32 v238, v240
	v_permlane16_swap_b32_e32 v239, v241
	global_store_dwordx4 v[246:247], v[238:241], off
	v_mul_f32_e32 v106, 0xbfb8aa3b, v114
	v_mul_f32_e32 v107, 0xbfb8aa3b, v115
	v_exp_f32_e32 v106, v106
	v_exp_f32_e32 v107, v107
	s_nop 0
	v_pk_add_f32 v[106:107], v[106:107], 1.0 op_sel_hi:[1,0]
	s_nop 0
	v_div_scale_f32 v108, s[10:11], v107, v107, v115
	v_rcp_f32_e32 v109, v108
	s_nop 0
	v_fma_f32 v110, -v108, v109, 1.0
	v_fmac_f32_e32 v109, v110, v109
	v_div_scale_f32 v110, vcc, v115, v107, v115
	v_mul_f32_e32 v111, v110, v109
	v_fma_f32 v112, -v108, v111, v110
	v_fmac_f32_e32 v111, v112, v109
	v_fma_f32 v108, -v108, v111, v110
	v_div_fmas_f32 v108, v108, v109, v111
	v_div_fixup_f32 v107, v108, v107, v115
	v_div_scale_f32 v108, s[10:11], v106, v106, v114
	v_rcp_f32_e32 v109, v108
	s_nop 0
	v_fma_f32 v110, -v108, v109, 1.0
	v_fmac_f32_e32 v109, v110, v109
	v_div_scale_f32 v110, vcc, v114, v106, v114
	v_mul_f32_e32 v111, v110, v109
	v_fma_f32 v112, -v108, v111, v110
	v_fmac_f32_e32 v111, v112, v109
	v_fma_f32 v108, -v108, v111, v110
	v_div_fmas_f32 v108, v108, v109, v111
	v_div_fixup_f32 v106, v108, v106, v114
	v_mul_f32_e32 v108, 0xbfb8aa3b, v116
	v_mul_f32_e32 v109, 0xbfb8aa3b, v117
	v_exp_f32_e32 v108, v108
	v_exp_f32_e32 v109, v109
	v_pk_mul_f32 v[106:107], v[118:119], v[106:107]
	v_pk_add_f32 v[108:109], v[108:109], 1.0 op_sel_hi:[1,0]
	s_nop 0
	v_div_scale_f32 v110, s[10:11], v109, v109, v117
	v_rcp_f32_e32 v111, v110
	v_cvt_pk_bf16_f32 v106, v106, v107
	v_fma_f32 v112, -v110, v111, 1.0
	v_fmac_f32_e32 v111, v112, v111
	v_div_scale_f32 v112, vcc, v117, v109, v117
	v_mul_f32_e32 v113, v112, v111
	v_fma_f32 v114, -v110, v113, v112
	v_fmac_f32_e32 v113, v114, v111
	v_fma_f32 v110, -v110, v113, v112
	v_div_fmas_f32 v110, v110, v111, v113
	v_div_fixup_f32 v109, v110, v109, v117
	v_div_scale_f32 v110, s[10:11], v108, v108, v116
	v_rcp_f32_e32 v111, v110
	s_nop 0
	v_fma_f32 v112, -v110, v111, 1.0
	v_fmac_f32_e32 v111, v112, v111
	v_div_scale_f32 v112, vcc, v116, v108, v116
	v_mul_f32_e32 v113, v112, v111
	v_fma_f32 v114, -v110, v113, v112
	v_fmac_f32_e32 v113, v114, v111
	v_fma_f32 v110, -v110, v113, v112
	v_div_fmas_f32 v110, v110, v111, v113
	v_div_fixup_f32 v108, v110, v108, v116
	v_pk_mul_f32 v[108:109], v[120:121], v[108:109]
	s_nop 0
	v_cvt_pk_bf16_f32 v107, v108, v109
	v_mov_b32_e32 v242, v106
	v_mov_b32_e32 v243, v107
	v_mul_f32_e32 v106, 0xbfb8aa3b, v102
	v_mul_f32_e32 v107, 0xbfb8aa3b, v103
	v_exp_f32_e32 v106, v106
	v_exp_f32_e32 v107, v107
	s_nop 0
	v_pk_add_f32 v[106:107], v[106:107], 1.0 op_sel_hi:[1,0]
	s_nop 0
	v_div_scale_f32 v108, s[10:11], v107, v107, v103
	v_rcp_f32_e32 v109, v108
	s_nop 0
	v_fma_f32 v110, -v108, v109, 1.0
	v_fmac_f32_e32 v109, v110, v109
	v_div_scale_f32 v110, vcc, v103, v107, v103
	v_mul_f32_e32 v111, v110, v109
	v_fma_f32 v112, -v108, v111, v110
	v_fmac_f32_e32 v111, v112, v109
	v_fma_f32 v108, -v108, v111, v110
	v_div_fmas_f32 v108, v108, v109, v111
	v_div_fixup_f32 v103, v108, v107, v103
	v_div_scale_f32 v107, s[10:11], v106, v106, v102
	v_rcp_f32_e32 v108, v107
	s_nop 0
	v_fma_f32 v109, -v107, v108, 1.0
	v_fmac_f32_e32 v108, v109, v108
	v_div_scale_f32 v109, vcc, v102, v106, v102
	v_mul_f32_e32 v110, v109, v108
	v_fma_f32 v111, -v107, v110, v109
	v_fmac_f32_e32 v110, v111, v108
	v_fma_f32 v107, -v107, v110, v109
	v_div_fmas_f32 v107, v107, v108, v110
	v_div_fixup_f32 v102, v107, v106, v102
	v_pk_mul_f32 v[98:99], v[98:99], v[102:103]
; DI float siluf_(float x) { return x / (1.f + __expf(-x)); }
; DI void st_bf4(bf16_t* dst, f32x4 v) { u32x2 o; o.x = pk2(v[0], v[1]); o.y = pk2(v[2], v[3]); *(u32x2*)dst = o; }
; DI void ffn1_item(const Params& p, int l, int item, bf16_t* lds) {
;     ...
;   for (int mi = 0; mi < 4; ++mi)
; #pragma unroll
;     for (int np = 0; np < 4; ++np) {
;       const int t = m0 + (wid >> 1) * 64 + mi * 16 + (lane & 15);
;       const int hcol = (((n0 + (wid & 1) * 128) >> 5) + np) * 16 + (lane >> 4) * 4;
;       f32x4 g = acc[mi][np * 2], u = acc[mi][np * 2 + 1], o;
; #pragma unroll
;       for (int r = 0; r < 4; ++r) o[r] = siluf_(g[r]) * u[r];
;       st_bf4(hid + (size_t)t * FH + hcol, o);
	v_mul_f32_e32 v102, 0xbfb8aa3b, v104
	v_mul_f32_e32 v103, 0xbfb8aa3b, v105
	v_exp_f32_e32 v102, v102
	v_exp_f32_e32 v103, v103
	v_cvt_pk_bf16_f32 v98, v98, v99
	v_pk_add_f32 v[102:103], v[102:103], 1.0 op_sel_hi:[1,0]
	s_nop 0
	v_div_scale_f32 v106, s[10:11], v103, v103, v105
	v_rcp_f32_e32 v107, v106
	s_nop 0
	v_fma_f32 v108, -v106, v107, 1.0
	v_fmac_f32_e32 v107, v108, v107
	v_div_scale_f32 v108, vcc, v105, v103, v105
	v_mul_f32_e32 v109, v108, v107
	v_fma_f32 v110, -v106, v109, v108
	v_fmac_f32_e32 v109, v110, v107
	v_fma_f32 v106, -v106, v109, v108
	v_div_fmas_f32 v106, v106, v107, v109
	v_div_fixup_f32 v103, v106, v103, v105
	v_div_scale_f32 v105, s[10:11], v102, v102, v104
	v_rcp_f32_e32 v106, v105
	s_nop 0
	v_fma_f32 v107, -v105, v106, 1.0
	v_fmac_f32_e32 v106, v107, v106
	v_div_scale_f32 v107, vcc, v104, v102, v104
	v_mul_f32_e32 v108, v107, v106
	v_fma_f32 v109, -v105, v108, v107
	v_fmac_f32_e32 v108, v109, v106
	v_fma_f32 v105, -v105, v108, v107
	v_div_fmas_f32 v105, v105, v106, v108
	v_div_fixup_f32 v102, v105, v102, v104
	v_pk_mul_f32 v[100:101], v[100:101], v[102:103]
	s_nop 0
	v_cvt_pk_bf16_f32 v99, v100, v101
	v_mul_f32_e32 v100, 0xbfb8aa3b, v90
	v_mul_f32_e32 v101, 0xbfb8aa3b, v91
	v_exp_f32_e32 v100, v100
	v_exp_f32_e32 v101, v101
	v_mov_b32_e32 v244, v98
	v_mov_b32_e32 v245, v99
	v_lshl_add_u64 v[246:247], v[124:125], 0, v[248:249]
	s_nop 0
	v_permlane16_swap_b32_e32 v242, v244
	v_permlane16_swap_b32_e32 v243, v245
	global_store_dwordx4 v[246:247], v[242:245], off offset:64
	v_or_b32_e32 v98, 16, v0
	v_mad_i64_i32 v[98:99], s[10:11], v98, s12, v[130:131]
	v_pk_add_f32 v[100:101], v[100:101], 1.0 op_sel_hi:[1,0]
	s_nop 0
	v_div_scale_f32 v102, s[10:11], v101, v101, v91
	v_rcp_f32_e32 v103, v102
	s_nop 0
	v_fma_f32 v104, -v102, v103, 1.0
	v_fmac_f32_e32 v103, v104, v103
	v_div_scale_f32 v104, vcc, v91, v101, v91
	v_mul_f32_e32 v105, v104, v103
	v_fma_f32 v106, -v102, v105, v104
	v_fmac_f32_e32 v105, v106, v103
	v_fma_f32 v102, -v102, v105, v104
	v_div_fmas_f32 v102, v102, v103, v105
	v_div_fixup_f32 v91, v102, v101, v91
	v_div_scale_f32 v101, s[10:11], v100, v100, v90
	v_rcp_f32_e32 v102, v101
	s_nop 0
	v_fma_f32 v103, -v101, v102, 1.0
	v_fmac_f32_e32 v102, v103, v102
	v_div_scale_f32 v103, vcc, v90, v100, v90
	v_mul_f32_e32 v104, v103, v102
	v_fma_f32 v105, -v101, v104, v103
	v_fmac_f32_e32 v104, v105, v102
	v_fma_f32 v101, -v101, v104, v103
	v_div_fmas_f32 v101, v101, v102, v104
	v_div_fixup_f32 v90, v101, v100, v90
	v_pk_mul_f32 v[94:95], v[94:95], v[90:91]
	v_mul_f32_e32 v90, 0xbfb8aa3b, v92
	v_mul_f32_e32 v91, 0xbfb8aa3b, v93
	v_exp_f32_e32 v90, v90
	v_exp_f32_e32 v91, v91
	v_cvt_pk_bf16_f32 v94, v94, v95
	v_pk_add_f32 v[90:91], v[90:91], 1.0 op_sel_hi:[1,0]
	s_nop 0
	v_div_scale_f32 v100, s[10:11], v91, v91, v93
	v_rcp_f32_e32 v101, v100
	s_nop 0
	v_fma_f32 v102, -v100, v101, 1.0
	v_fmac_f32_e32 v101, v102, v101
	v_div_scale_f32 v102, vcc, v93, v91, v93
	v_mul_f32_e32 v103, v102, v101
	v_fma_f32 v104, -v100, v103, v102
	v_fmac_f32_e32 v103, v104, v101
	v_fma_f32 v100, -v100, v103, v102
	v_div_fmas_f32 v100, v100, v101, v103
	v_div_fixup_f32 v91, v100, v91, v93
	v_div_scale_f32 v93, s[10:11], v90, v90, v92
	v_rcp_f32_e32 v100, v93
	s_nop 0
	v_fma_f32 v101, -v93, v100, 1.0
	v_fmac_f32_e32 v100, v101, v100
	v_div_scale_f32 v101, vcc, v92, v90, v92
	v_mul_f32_e32 v102, v101, v100
	v_fma_f32 v103, -v93, v102, v101
	v_fmac_f32_e32 v102, v103, v100
	v_fma_f32 v93, -v93, v102, v101
	v_div_fmas_f32 v93, v93, v100, v102
	v_div_fixup_f32 v90, v93, v90, v92
	v_pk_mul_f32 v[92:93], v[96:97], v[90:91]
	v_lshl_add_u64 v[90:91], v[98:99], 0, v[122:123]
	v_cvt_pk_bf16_f32 v95, v92, v93
	v_mul_f32_e32 v92, 0xbfb8aa3b, v74
	v_mul_f32_e32 v93, 0xbfb8aa3b, v75
	v_exp_f32_e32 v92, v92
	v_exp_f32_e32 v93, v93
	v_mov_b32_e32 v238, v94
	v_mov_b32_e32 v239, v95
	v_pk_add_f32 v[92:93], v[92:93], 1.0 op_sel_hi:[1,0]
	s_nop 0
	v_div_scale_f32 v94, s[10:11], v93, v93, v75
	v_rcp_f32_e32 v95, v94
	s_nop 0
	v_fma_f32 v96, -v94, v95, 1.0
	v_fmac_f32_e32 v95, v96, v95
	v_div_scale_f32 v96, vcc, v75, v93, v75
	v_mul_f32_e32 v97, v96, v95
	v_fma_f32 v98, -v94, v97, v96
	v_fmac_f32_e32 v97, v98, v95
	v_fma_f32 v94, -v94, v97, v96
	v_div_fmas_f32 v94, v94, v95, v97
	v_div_fixup_f32 v75, v94, v93, v75
	v_div_scale_f32 v93, s[10:11], v92, v92, v74
	v_rcp_f32_e32 v94, v93
	s_nop 0
	v_fma_f32 v95, -v93, v94, 1.0
	v_fmac_f32_e32 v94, v95, v94
	v_div_scale_f32 v95, vcc, v74, v92, v74
	v_mul_f32_e32 v96, v95, v94
	v_fma_f32 v97, -v93, v96, v95
	v_fmac_f32_e32 v96, v97, v94
	v_fma_f32 v93, -v93, v96, v95
	v_div_fmas_f32 v93, v93, v94, v96
	v_div_fixup_f32 v74, v93, v92, v74
	v_pk_mul_f32 v[74:75], v[78:79], v[74:75]
	v_mul_f32_e32 v78, 0xbfb8aa3b, v76
	v_mul_f32_e32 v79, 0xbfb8aa3b, v77
	v_exp_f32_e32 v78, v78
	v_exp_f32_e32 v79, v79
	v_cvt_pk_bf16_f32 v74, v74, v75
	v_pk_add_f32 v[78:79], v[78:79], 1.0 op_sel_hi:[1,0]
	s_nop 0
	v_div_scale_f32 v92, s[10:11], v79, v79, v77
	v_rcp_f32_e32 v93, v92
	s_nop 0
	v_fma_f32 v94, -v92, v93, 1.0
	v_fmac_f32_e32 v93, v94, v93
	v_div_scale_f32 v94, vcc, v77, v79, v77
	v_mul_f32_e32 v95, v94, v93
	v_fma_f32 v96, -v92, v95, v94
	v_fmac_f32_e32 v95, v96, v93
	v_fma_f32 v92, -v92, v95, v94
	v_div_fmas_f32 v92, v92, v93, v95
	v_div_fixup_f32 v77, v92, v79, v77
	v_div_scale_f32 v79, s[10:11], v78, v78, v76
	v_rcp_f32_e32 v92, v79
	s_nop 0
	v_fma_f32 v93, -v79, v92, 1.0
	v_fmac_f32_e32 v92, v93, v92
	v_div_scale_f32 v93, vcc, v76, v78, v76
	v_mul_f32_e32 v94, v93, v92
	v_fma_f32 v95, -v79, v94, v93
	v_fmac_f32_e32 v94, v95, v92
	v_fma_f32 v79, -v79, v94, v93
	v_div_fmas_f32 v79, v79, v92, v94
	v_div_fixup_f32 v76, v79, v78, v76
; DI float siluf_(float x) { return x / (1.f + __expf(-x)); }
; DI void st_bf4(bf16_t* dst, f32x4 v) { u32x2 o; o.x = pk2(v[0], v[1]); o.y = pk2(v[2], v[3]); *(u32x2*)dst = o; }
; DI void ffn1_item(const Params& p, int l, int item, bf16_t* lds) {
;     ...
;   for (int mi = 0; mi < 4; ++mi)
; #pragma unroll
;     for (int np = 0; np < 4; ++np) {
;       const int t = m0 + (wid >> 1) * 64 + mi * 16 + (lane & 15);
;       const int hcol = (((n0 + (wid & 1) * 128) >> 5) + np) * 16 + (lane >> 4) * 4;
;       f32x4 g = acc[mi][np * 2], u = acc[mi][np * 2 + 1], o;
; #pragma unroll
;       for (int r = 0; r < 4; ++r) o[r] = siluf_(g[r]) * u[r];
;       st_bf4(hid + (size_t)t * FH + hcol, o);
	v_pk_mul_f32 v[76:77], v[80:81], v[76:77]
	s_nop 0
	v_cvt_pk_bf16_f32 v75, v76, v77
	v_mov_b32_e32 v240, v74
	v_mov_b32_e32 v241, v75
	v_lshl_add_u64 v[246:247], v[90:91], 0, v[248:249]
	s_nop 0
	v_permlane16_swap_b32_e32 v238, v240
	v_permlane16_swap_b32_e32 v239, v241
	global_store_dwordx4 v[246:247], v[238:241], off
	v_mul_f32_e32 v74, 0xbfb8aa3b, v82
	v_mul_f32_e32 v75, 0xbfb8aa3b, v83
	v_exp_f32_e32 v74, v74
	v_exp_f32_e32 v75, v75
	s_nop 0
	v_pk_add_f32 v[74:75], v[74:75], 1.0 op_sel_hi:[1,0]
	s_nop 0
	v_div_scale_f32 v76, s[10:11], v75, v75, v83
	v_rcp_f32_e32 v77, v76
	s_nop 0
	v_fma_f32 v78, -v76, v77, 1.0
	v_fmac_f32_e32 v77, v78, v77
	v_div_scale_f32 v78, vcc, v83, v75, v83
	v_mul_f32_e32 v79, v78, v77
	v_fma_f32 v80, -v76, v79, v78
	v_fmac_f32_e32 v79, v80, v77
	v_fma_f32 v76, -v76, v79, v78
	v_div_fmas_f32 v76, v76, v77, v79
	v_div_fixup_f32 v75, v76, v75, v83
	v_div_scale_f32 v76, s[10:11], v74, v74, v82
	v_rcp_f32_e32 v77, v76
	s_nop 0
	v_fma_f32 v78, -v76, v77, 1.0
	v_fmac_f32_e32 v77, v78, v77
	v_div_scale_f32 v78, vcc, v82, v74, v82
	v_mul_f32_e32 v79, v78, v77
	v_fma_f32 v80, -v76, v79, v78
	v_fmac_f32_e32 v79, v80, v77
	v_fma_f32 v76, -v76, v79, v78
	v_div_fmas_f32 v76, v76, v77, v79
	v_div_fixup_f32 v74, v76, v74, v82
	v_mul_f32_e32 v76, 0xbfb8aa3b, v84
	v_mul_f32_e32 v77, 0xbfb8aa3b, v85
	v_exp_f32_e32 v76, v76
	v_exp_f32_e32 v77, v77
	v_pk_mul_f32 v[74:75], v[86:87], v[74:75]
	v_pk_add_f32 v[76:77], v[76:77], 1.0 op_sel_hi:[1,0]
	s_nop 0
	v_div_scale_f32 v78, s[10:11], v77, v77, v85
	v_rcp_f32_e32 v79, v78
	v_cvt_pk_bf16_f32 v74, v74, v75
	v_fma_f32 v80, -v78, v79, 1.0
	v_fmac_f32_e32 v79, v80, v79
	v_div_scale_f32 v80, vcc, v85, v77, v85
	v_mul_f32_e32 v81, v80, v79
	v_fma_f32 v82, -v78, v81, v80
	v_fmac_f32_e32 v81, v82, v79
	v_fma_f32 v78, -v78, v81, v80
	v_div_fmas_f32 v78, v78, v79, v81
	v_div_fixup_f32 v77, v78, v77, v85
	v_div_scale_f32 v78, s[10:11], v76, v76, v84
	v_rcp_f32_e32 v79, v78
	s_nop 0
	v_fma_f32 v80, -v78, v79, 1.0
	v_fmac_f32_e32 v79, v80, v79
	v_div_scale_f32 v80, vcc, v84, v76, v84
	v_mul_f32_e32 v81, v80, v79
	v_fma_f32 v82, -v78, v81, v80
	v_fmac_f32_e32 v81, v82, v79
	v_fma_f32 v78, -v78, v81, v80
	v_div_fmas_f32 v78, v78, v79, v81
	v_div_fixup_f32 v76, v78, v76, v84
	v_pk_mul_f32 v[76:77], v[88:89], v[76:77]
	s_nop 0
	v_cvt_pk_bf16_f32 v75, v76, v77
	v_mov_b32_e32 v242, v74
	v_mov_b32_e32 v243, v75
	v_mul_f32_e32 v74, 0xbfb8aa3b, v70
	v_mul_f32_e32 v75, 0xbfb8aa3b, v71
	v_exp_f32_e32 v74, v74
	v_exp_f32_e32 v75, v75
	s_nop 0
	v_pk_add_f32 v[74:75], v[74:75], 1.0 op_sel_hi:[1,0]
	s_nop 0
	v_div_scale_f32 v76, s[10:11], v75, v75, v71
	v_rcp_f32_e32 v77, v76
	s_nop 0
	v_fma_f32 v78, -v76, v77, 1.0
	v_fmac_f32_e32 v77, v78, v77
	v_div_scale_f32 v78, vcc, v71, v75, v71
	v_mul_f32_e32 v79, v78, v77
	v_fma_f32 v80, -v76, v79, v78
	v_fmac_f32_e32 v79, v80, v77
	v_fma_f32 v76, -v76, v79, v78
	v_div_fmas_f32 v76, v76, v77, v79
	v_div_fixup_f32 v71, v76, v75, v71
	v_div_scale_f32 v75, s[10:11], v74, v74, v70
	v_rcp_f32_e32 v76, v75
	s_nop 0
	v_fma_f32 v77, -v75, v76, 1.0
	v_fmac_f32_e32 v76, v77, v76
	v_div_scale_f32 v77, vcc, v70, v74, v70
	v_mul_f32_e32 v78, v77, v76
	v_fma_f32 v79, -v75, v78, v77
	v_fmac_f32_e32 v78, v79, v76
	v_fma_f32 v75, -v75, v78, v77
	v_div_fmas_f32 v75, v75, v76, v78
	v_div_fixup_f32 v70, v75, v74, v70
	v_pk_mul_f32 v[66:67], v[66:67], v[70:71]
	v_mul_f32_e32 v70, 0xbfb8aa3b, v72
	v_mul_f32_e32 v71, 0xbfb8aa3b, v73
	v_exp_f32_e32 v70, v70
	v_exp_f32_e32 v71, v71
	v_cvt_pk_bf16_f32 v66, v66, v67
	v_pk_add_f32 v[70:71], v[70:71], 1.0 op_sel_hi:[1,0]
	s_nop 0
	v_div_scale_f32 v74, s[10:11], v71, v71, v73
	v_rcp_f32_e32 v75, v74
	s_nop 0
	v_fma_f32 v76, -v74, v75, 1.0
	v_fmac_f32_e32 v75, v76, v75
	v_div_scale_f32 v76, vcc, v73, v71, v73
	v_mul_f32_e32 v77, v76, v75
	v_fma_f32 v78, -v74, v77, v76
	v_fmac_f32_e32 v77, v78, v75
	v_fma_f32 v74, -v74, v77, v76
	v_div_fmas_f32 v74, v74, v75, v77
	v_div_fixup_f32 v71, v74, v71, v73
	v_div_scale_f32 v73, s[10:11], v70, v70, v72
	v_rcp_f32_e32 v74, v73
	s_nop 0
	v_fma_f32 v75, -v73, v74, 1.0
	v_fmac_f32_e32 v74, v75, v74
	v_div_scale_f32 v75, vcc, v72, v70, v72
	v_mul_f32_e32 v76, v75, v74
	v_fma_f32 v77, -v73, v76, v75
	v_fmac_f32_e32 v76, v77, v74
	v_fma_f32 v73, -v73, v76, v75
	v_div_fmas_f32 v73, v73, v74, v76
	v_div_fixup_f32 v70, v73, v70, v72
	v_pk_mul_f32 v[68:69], v[68:69], v[70:71]
	s_nop 0
	v_cvt_pk_bf16_f32 v67, v68, v69
	v_mul_f32_e32 v68, 0xbfb8aa3b, v58
	v_mul_f32_e32 v69, 0xbfb8aa3b, v59
	v_exp_f32_e32 v68, v68
	v_exp_f32_e32 v69, v69
	v_mov_b32_e32 v244, v66
	v_mov_b32_e32 v245, v67
	v_lshl_add_u64 v[246:247], v[90:91], 0, v[248:249]
	s_nop 0
	v_permlane16_swap_b32_e32 v242, v244
	v_permlane16_swap_b32_e32 v243, v245
	global_store_dwordx4 v[246:247], v[242:245], off offset:64
	v_or_b32_e32 v66, 32, v0
	v_mad_i64_i32 v[66:67], s[10:11], v66, s12, v[130:131]
	v_pk_add_f32 v[68:69], v[68:69], 1.0 op_sel_hi:[1,0]
	v_or_b32_e32 v0, 48, v0
	v_div_scale_f32 v70, s[10:11], v69, v69, v59
	v_rcp_f32_e32 v71, v70
	s_nop 0
	v_fma_f32 v72, -v70, v71, 1.0
	v_fmac_f32_e32 v71, v72, v71
	v_div_scale_f32 v72, vcc, v59, v69, v59
	v_mul_f32_e32 v73, v72, v71
	v_fma_f32 v74, -v70, v73, v72
	v_fmac_f32_e32 v73, v74, v71
	v_fma_f32 v70, -v70, v73, v72
	v_div_fmas_f32 v70, v70, v71, v73
	v_div_fixup_f32 v59, v70, v69, v59
	v_div_scale_f32 v69, s[10:11], v68, v68, v58
	v_rcp_f32_e32 v70, v69
	s_nop 0
	v_fma_f32 v71, -v69, v70, 1.0
	v_fmac_f32_e32 v70, v71, v70
	v_div_scale_f32 v71, vcc, v58, v68, v58
	v_mul_f32_e32 v72, v71, v70
	v_fma_f32 v73, -v69, v72, v71
	v_fmac_f32_e32 v72, v73, v70
	v_fma_f32 v69, -v69, v72, v71
	v_div_fmas_f32 v69, v69, v70, v72
; DI float siluf_(float x) { return x / (1.f + __expf(-x)); }
; DI void st_bf4(bf16_t* dst, f32x4 v) { u32x2 o; o.x = pk2(v[0], v[1]); o.y = pk2(v[2], v[3]); *(u32x2*)dst = o; }
; DI void ffn1_item(const Params& p, int l, int item, bf16_t* lds) {
;     ...
;   for (int mi = 0; mi < 4; ++mi)
; #pragma unroll
;     for (int np = 0; np < 4; ++np) {
;       const int t = m0 + (wid >> 1) * 64 + mi * 16 + (lane & 15);
;       const int hcol = (((n0 + (wid & 1) * 128) >> 5) + np) * 16 + (lane >> 4) * 4;
;       f32x4 g = acc[mi][np * 2], u = acc[mi][np * 2 + 1], o;
; #pragma unroll
;       for (int r = 0; r < 4; ++r) o[r] = siluf_(g[r]) * u[r];
;       st_bf4(hid + (size_t)t * FH + hcol, o);
	v_div_fixup_f32 v58, v69, v68, v58
	v_pk_mul_f32 v[62:63], v[62:63], v[58:59]
	v_mul_f32_e32 v58, 0xbfb8aa3b, v60
	v_mul_f32_e32 v59, 0xbfb8aa3b, v61
	v_exp_f32_e32 v58, v58
	v_exp_f32_e32 v59, v59
	v_cvt_pk_bf16_f32 v62, v62, v63
	v_pk_add_f32 v[58:59], v[58:59], 1.0 op_sel_hi:[1,0]
	s_nop 0
	v_div_scale_f32 v68, s[10:11], v59, v59, v61
	v_rcp_f32_e32 v69, v68
	s_nop 0
	v_fma_f32 v70, -v68, v69, 1.0
	v_fmac_f32_e32 v69, v70, v69
	v_div_scale_f32 v70, vcc, v61, v59, v61
	v_mul_f32_e32 v71, v70, v69
	v_fma_f32 v72, -v68, v71, v70
	v_fmac_f32_e32 v71, v72, v69
	v_fma_f32 v68, -v68, v71, v70
	v_div_fmas_f32 v68, v68, v69, v71
	v_div_fixup_f32 v59, v68, v59, v61
	v_div_scale_f32 v61, s[10:11], v58, v58, v60
	v_rcp_f32_e32 v68, v61
	s_nop 0
	v_fma_f32 v69, -v61, v68, 1.0
	v_fmac_f32_e32 v68, v69, v68
	v_div_scale_f32 v69, vcc, v60, v58, v60
	v_mul_f32_e32 v70, v69, v68
	v_fma_f32 v71, -v61, v70, v69
	v_fmac_f32_e32 v70, v71, v68
	v_fma_f32 v61, -v61, v70, v69
	v_div_fmas_f32 v61, v61, v68, v70
	v_div_fixup_f32 v58, v61, v58, v60
	v_pk_mul_f32 v[60:61], v[64:65], v[58:59]
	v_lshl_add_u64 v[58:59], v[66:67], 0, v[122:123]
	v_cvt_pk_bf16_f32 v63, v60, v61
	v_mul_f32_e32 v60, 0xbfb8aa3b, v42
	v_mul_f32_e32 v61, 0xbfb8aa3b, v43
	v_exp_f32_e32 v60, v60
	v_exp_f32_e32 v61, v61
	v_mov_b32_e32 v238, v62
	v_mov_b32_e32 v239, v63
	v_pk_add_f32 v[60:61], v[60:61], 1.0 op_sel_hi:[1,0]
	s_nop 0
	v_div_scale_f32 v62, s[10:11], v61, v61, v43
	v_rcp_f32_e32 v63, v62
	s_nop 0
	v_fma_f32 v64, -v62, v63, 1.0
	v_fmac_f32_e32 v63, v64, v63
	v_div_scale_f32 v64, vcc, v43, v61, v43
	v_mul_f32_e32 v65, v64, v63
	v_fma_f32 v66, -v62, v65, v64
	v_fmac_f32_e32 v65, v66, v63
	v_fma_f32 v62, -v62, v65, v64
	v_div_fmas_f32 v62, v62, v63, v65
	v_div_fixup_f32 v43, v62, v61, v43
	v_div_scale_f32 v61, s[10:11], v60, v60, v42
	v_rcp_f32_e32 v62, v61
	s_nop 0
	v_fma_f32 v63, -v61, v62, 1.0
	v_fmac_f32_e32 v62, v63, v62
	v_div_scale_f32 v63, vcc, v42, v60, v42
	v_mul_f32_e32 v64, v63, v62
	v_fma_f32 v65, -v61, v64, v63
	v_fmac_f32_e32 v64, v65, v62
	v_fma_f32 v61, -v61, v64, v63
	v_div_fmas_f32 v61, v61, v62, v64
	v_div_fixup_f32 v42, v61, v60, v42
	v_pk_mul_f32 v[42:43], v[46:47], v[42:43]
	v_mul_f32_e32 v46, 0xbfb8aa3b, v44
	v_mul_f32_e32 v47, 0xbfb8aa3b, v45
	v_exp_f32_e32 v46, v46
	v_exp_f32_e32 v47, v47
	v_cvt_pk_bf16_f32 v42, v42, v43
	v_pk_add_f32 v[46:47], v[46:47], 1.0 op_sel_hi:[1,0]
	s_nop 0
	v_div_scale_f32 v60, s[10:11], v47, v47, v45
	v_rcp_f32_e32 v61, v60
	s_nop 0
	v_fma_f32 v62, -v60, v61, 1.0
	v_fmac_f32_e32 v61, v62, v61
	v_div_scale_f32 v62, vcc, v45, v47, v45
	v_mul_f32_e32 v63, v62, v61
	v_fma_f32 v64, -v60, v63, v62
	v_fmac_f32_e32 v63, v64, v61
	v_fma_f32 v60, -v60, v63, v62
	v_div_fmas_f32 v60, v60, v61, v63
	v_div_fixup_f32 v45, v60, v47, v45
	v_div_scale_f32 v47, s[10:11], v46, v46, v44
	v_rcp_f32_e32 v60, v47
	s_nop 0
	v_fma_f32 v61, -v47, v60, 1.0
	v_fmac_f32_e32 v60, v61, v60
	v_div_scale_f32 v61, vcc, v44, v46, v44
	v_mul_f32_e32 v62, v61, v60
	v_fma_f32 v63, -v47, v62, v61
	v_fmac_f32_e32 v62, v63, v60
	v_fma_f32 v47, -v47, v62, v61
	v_div_fmas_f32 v47, v47, v60, v62
	v_div_fixup_f32 v44, v47, v46, v44
	v_pk_mul_f32 v[44:45], v[48:49], v[44:45]
	s_nop 0
	v_cvt_pk_bf16_f32 v43, v44, v45
	v_mov_b32_e32 v240, v42
	v_mov_b32_e32 v241, v43
	v_lshl_add_u64 v[246:247], v[58:59], 0, v[248:249]
	s_nop 0
	v_permlane16_swap_b32_e32 v238, v240
	v_permlane16_swap_b32_e32 v239, v241
	global_store_dwordx4 v[246:247], v[238:241], off
	v_mul_f32_e32 v42, 0xbfb8aa3b, v50
	v_mul_f32_e32 v43, 0xbfb8aa3b, v51
	v_exp_f32_e32 v42, v42
	v_exp_f32_e32 v43, v43
	s_nop 0
	v_pk_add_f32 v[42:43], v[42:43], 1.0 op_sel_hi:[1,0]
	s_nop 0
	v_div_scale_f32 v44, s[10:11], v43, v43, v51
	v_rcp_f32_e32 v45, v44
	s_nop 0
	v_fma_f32 v46, -v44, v45, 1.0
	v_fmac_f32_e32 v45, v46, v45
	v_div_scale_f32 v46, vcc, v51, v43, v51
	v_mul_f32_e32 v47, v46, v45
	v_fma_f32 v48, -v44, v47, v46
	v_fmac_f32_e32 v47, v48, v45
	v_fma_f32 v44, -v44, v47, v46
	v_div_fmas_f32 v44, v44, v45, v47
	v_div_fixup_f32 v43, v44, v43, v51
	v_div_scale_f32 v44, s[10:11], v42, v42, v50
	v_rcp_f32_e32 v45, v44
	s_nop 0
	v_fma_f32 v46, -v44, v45, 1.0
	v_fmac_f32_e32 v45, v46, v45
	v_div_scale_f32 v46, vcc, v50, v42, v50
	v_mul_f32_e32 v47, v46, v45
	v_fma_f32 v48, -v44, v47, v46
	v_fmac_f32_e32 v47, v48, v45
	v_fma_f32 v44, -v44, v47, v46
	v_div_fmas_f32 v44, v44, v45, v47
	v_div_fixup_f32 v42, v44, v42, v50
	v_mul_f32_e32 v44, 0xbfb8aa3b, v52
	v_mul_f32_e32 v45, 0xbfb8aa3b, v53
	v_exp_f32_e32 v44, v44
	v_exp_f32_e32 v45, v45
	v_pk_mul_f32 v[42:43], v[54:55], v[42:43]
	v_pk_add_f32 v[44:45], v[44:45], 1.0 op_sel_hi:[1,0]
	s_nop 0
	v_div_scale_f32 v46, s[10:11], v45, v45, v53
	v_rcp_f32_e32 v47, v46
	v_cvt_pk_bf16_f32 v42, v42, v43
	v_fma_f32 v48, -v46, v47, 1.0
	v_fmac_f32_e32 v47, v48, v47
	v_div_scale_f32 v48, vcc, v53, v45, v53
	v_mul_f32_e32 v49, v48, v47
	v_fma_f32 v50, -v46, v49, v48
	v_fmac_f32_e32 v49, v50, v47
	v_fma_f32 v46, -v46, v49, v48
	v_div_fmas_f32 v46, v46, v47, v49
	v_div_fixup_f32 v45, v46, v45, v53
	v_div_scale_f32 v46, s[10:11], v44, v44, v52
	v_rcp_f32_e32 v47, v46
	s_nop 0
	v_fma_f32 v48, -v46, v47, 1.0
	v_fmac_f32_e32 v47, v48, v47
	v_div_scale_f32 v48, vcc, v52, v44, v52
	v_mul_f32_e32 v49, v48, v47
	v_fma_f32 v50, -v46, v49, v48
	v_fmac_f32_e32 v49, v50, v47
	v_fma_f32 v46, -v46, v49, v48
	v_div_fmas_f32 v46, v46, v47, v49
	v_div_fixup_f32 v44, v46, v44, v52
	v_pk_mul_f32 v[44:45], v[56:57], v[44:45]
	s_nop 0
	v_cvt_pk_bf16_f32 v43, v44, v45
	v_mov_b32_e32 v242, v42
	v_mov_b32_e32 v243, v43
	v_mul_f32_e32 v42, 0xbfb8aa3b, v38
	v_mul_f32_e32 v43, 0xbfb8aa3b, v39
	v_exp_f32_e32 v42, v42
; DI float siluf_(float x) { return x / (1.f + __expf(-x)); }
; DI void st_bf4(bf16_t* dst, f32x4 v) { u32x2 o; o.x = pk2(v[0], v[1]); o.y = pk2(v[2], v[3]); *(u32x2*)dst = o; }
; DI void ffn1_item(const Params& p, int l, int item, bf16_t* lds) {
;     ...
;   for (int mi = 0; mi < 4; ++mi)
; #pragma unroll
;     for (int np = 0; np < 4; ++np) {
;       const int t = m0 + (wid >> 1) * 64 + mi * 16 + (lane & 15);
;       const int hcol = (((n0 + (wid & 1) * 128) >> 5) + np) * 16 + (lane >> 4) * 4;
;       f32x4 g = acc[mi][np * 2], u = acc[mi][np * 2 + 1], o;
; #pragma unroll
;       for (int r = 0; r < 4; ++r) o[r] = siluf_(g[r]) * u[r];
;       st_bf4(hid + (size_t)t * FH + hcol, o);
	v_exp_f32_e32 v43, v43
	s_nop 0
	v_pk_add_f32 v[42:43], v[42:43], 1.0 op_sel_hi:[1,0]
	s_nop 0
	v_div_scale_f32 v44, s[10:11], v43, v43, v39
	v_rcp_f32_e32 v45, v44
	s_nop 0
	v_fma_f32 v46, -v44, v45, 1.0
	v_fmac_f32_e32 v45, v46, v45
	v_div_scale_f32 v46, vcc, v39, v43, v39
	v_mul_f32_e32 v47, v46, v45
	v_fma_f32 v48, -v44, v47, v46
	v_fmac_f32_e32 v47, v48, v45
	v_fma_f32 v44, -v44, v47, v46
	v_div_fmas_f32 v44, v44, v45, v47
	v_div_fixup_f32 v39, v44, v43, v39
	v_div_scale_f32 v43, s[10:11], v42, v42, v38
	v_rcp_f32_e32 v44, v43
	s_nop 0
	v_fma_f32 v45, -v43, v44, 1.0
	v_fmac_f32_e32 v44, v45, v44
	v_div_scale_f32 v45, vcc, v38, v42, v38
	v_mul_f32_e32 v46, v45, v44
	v_fma_f32 v47, -v43, v46, v45
	v_fmac_f32_e32 v46, v47, v44
	v_fma_f32 v43, -v43, v46, v45
	v_div_fmas_f32 v43, v43, v44, v46
	v_div_fixup_f32 v38, v43, v42, v38
	v_pk_mul_f32 v[34:35], v[34:35], v[38:39]
	v_mul_f32_e32 v38, 0xbfb8aa3b, v40
	v_mul_f32_e32 v39, 0xbfb8aa3b, v41
	v_exp_f32_e32 v38, v38
	v_exp_f32_e32 v39, v39
	v_cvt_pk_bf16_f32 v34, v34, v35
	v_pk_add_f32 v[38:39], v[38:39], 1.0 op_sel_hi:[1,0]
	s_nop 0
	v_div_scale_f32 v42, s[10:11], v39, v39, v41
	v_rcp_f32_e32 v43, v42
	s_nop 0
	v_fma_f32 v44, -v42, v43, 1.0
	v_fmac_f32_e32 v43, v44, v43
	v_div_scale_f32 v44, vcc, v41, v39, v41
	v_mul_f32_e32 v45, v44, v43
	v_fma_f32 v46, -v42, v45, v44
	v_fmac_f32_e32 v45, v46, v43
	v_fma_f32 v42, -v42, v45, v44
	v_div_fmas_f32 v42, v42, v43, v45
	v_div_fixup_f32 v39, v42, v39, v41
	v_div_scale_f32 v41, s[10:11], v38, v38, v40
	v_rcp_f32_e32 v42, v41
	s_nop 0
	v_fma_f32 v43, -v41, v42, 1.0
	v_fmac_f32_e32 v42, v43, v42
	v_div_scale_f32 v43, vcc, v40, v38, v40
	v_mul_f32_e32 v44, v43, v42
	v_fma_f32 v45, -v41, v44, v43
	v_fmac_f32_e32 v44, v45, v42
	v_fma_f32 v41, -v41, v44, v43
	v_div_fmas_f32 v41, v41, v42, v44
	v_div_fixup_f32 v38, v41, v38, v40
	v_pk_mul_f32 v[36:37], v[36:37], v[38:39]
	s_nop 0
	v_cvt_pk_bf16_f32 v35, v36, v37
	v_mov_b32_e32 v244, v34
	v_mov_b32_e32 v245, v35
	v_lshl_add_u64 v[246:247], v[58:59], 0, v[248:249]
	s_nop 0
	v_permlane16_swap_b32_e32 v242, v244
	v_permlane16_swap_b32_e32 v243, v245
	global_store_dwordx4 v[246:247], v[242:245], off offset:64
	v_mad_i64_i32 v[34:35], s[10:11], v0, s12, v[130:131]
	v_mul_f32_e32 v0, 0xbfb8aa3b, v26
	v_exp_f32_e32 v36, v0
	v_mul_f32_e32 v0, 0xbfb8aa3b, v27
	v_exp_f32_e32 v37, v0
	s_nop 0
	v_pk_add_f32 v[36:37], v[36:37], 1.0 op_sel_hi:[1,0]
	s_nop 0
	v_div_scale_f32 v0, s[10:11], v37, v37, v27
	v_rcp_f32_e32 v38, v0
	s_nop 0
	v_fma_f32 v39, -v0, v38, 1.0
	v_fmac_f32_e32 v38, v39, v38
	v_div_scale_f32 v39, vcc, v27, v37, v27
	v_mul_f32_e32 v40, v39, v38
	v_fma_f32 v41, -v0, v40, v39
	v_fmac_f32_e32 v40, v41, v38
	v_fma_f32 v0, -v0, v40, v39
	v_div_fmas_f32 v0, v0, v38, v40
	v_div_fixup_f32 v27, v0, v37, v27
	v_div_scale_f32 v0, s[10:11], v36, v36, v26
	v_rcp_f32_e32 v37, v0
	s_nop 0
	v_fma_f32 v38, -v0, v37, 1.0
	v_fmac_f32_e32 v37, v38, v37
	v_div_scale_f32 v38, vcc, v26, v36, v26
	v_mul_f32_e32 v39, v38, v37
	v_fma_f32 v40, -v0, v39, v38
	v_fmac_f32_e32 v39, v40, v37
	v_fma_f32 v0, -v0, v39, v38
	v_div_fmas_f32 v0, v0, v37, v39
	v_div_fixup_f32 v26, v0, v36, v26
	v_mul_f32_e32 v0, 0xbfb8aa3b, v28
	v_pk_mul_f32 v[30:31], v[30:31], v[26:27]
	v_exp_f32_e32 v26, v0
	v_mul_f32_e32 v0, 0xbfb8aa3b, v29
	v_exp_f32_e32 v27, v0
	v_cvt_pk_bf16_f32 v30, v30, v31
	v_pk_add_f32 v[26:27], v[26:27], 1.0 op_sel_hi:[1,0]
	s_nop 0
	v_div_scale_f32 v0, s[10:11], v27, v27, v29
	v_rcp_f32_e32 v36, v0
	s_nop 0
	v_fma_f32 v37, -v0, v36, 1.0
	v_fmac_f32_e32 v36, v37, v36
	v_div_scale_f32 v37, vcc, v29, v27, v29
	v_mul_f32_e32 v38, v37, v36
	v_fma_f32 v39, -v0, v38, v37
	v_fmac_f32_e32 v38, v39, v36
	v_fma_f32 v0, -v0, v38, v37
	v_div_fmas_f32 v0, v0, v36, v38
	v_div_fixup_f32 v27, v0, v27, v29
	v_div_scale_f32 v0, s[10:11], v26, v26, v28
	v_rcp_f32_e32 v29, v0
	s_nop 0
	v_fma_f32 v36, -v0, v29, 1.0
	v_fmac_f32_e32 v29, v36, v29
	v_div_scale_f32 v36, vcc, v28, v26, v28
	v_mul_f32_e32 v37, v36, v29
	v_fma_f32 v38, -v0, v37, v36
	v_fmac_f32_e32 v37, v38, v29
	v_fma_f32 v0, -v0, v37, v36
	v_div_fmas_f32 v0, v0, v29, v37
	v_div_fixup_f32 v26, v0, v26, v28
	v_pk_mul_f32 v[28:29], v[32:33], v[26:27]
	v_mul_f32_e32 v0, 0xbfb8aa3b, v10
	v_cvt_pk_bf16_f32 v31, v28, v29
	v_exp_f32_e32 v28, v0
	v_mul_f32_e32 v0, 0xbfb8aa3b, v11
	v_exp_f32_e32 v29, v0
	v_lshl_add_u64 v[26:27], v[34:35], 0, v[122:123]
	v_mov_b32_e32 v238, v30
	v_mov_b32_e32 v239, v31
	v_pk_add_f32 v[28:29], v[28:29], 1.0 op_sel_hi:[1,0]
	s_nop 0
	v_div_scale_f32 v0, s[10:11], v29, v29, v11
	v_rcp_f32_e32 v30, v0
	s_nop 0
	v_fma_f32 v31, -v0, v30, 1.0
	v_fmac_f32_e32 v30, v31, v30
	v_div_scale_f32 v31, vcc, v11, v29, v11
	v_mul_f32_e32 v32, v31, v30
	v_fma_f32 v33, -v0, v32, v31
	v_fmac_f32_e32 v32, v33, v30
	v_fma_f32 v0, -v0, v32, v31
	v_div_fmas_f32 v0, v0, v30, v32
	v_div_fixup_f32 v11, v0, v29, v11
	v_div_scale_f32 v0, s[10:11], v28, v28, v10
	v_rcp_f32_e32 v29, v0
	s_nop 0
	v_fma_f32 v30, -v0, v29, 1.0
	v_fmac_f32_e32 v29, v30, v29
	v_div_scale_f32 v30, vcc, v10, v28, v10
	v_mul_f32_e32 v31, v30, v29
	v_fma_f32 v32, -v0, v31, v30
	v_fmac_f32_e32 v31, v32, v29
	v_fma_f32 v0, -v0, v31, v30
	v_div_fmas_f32 v0, v0, v29, v31
	v_div_fixup_f32 v10, v0, v28, v10
	v_mul_f32_e32 v0, 0xbfb8aa3b, v12
	v_pk_mul_f32 v[10:11], v[14:15], v[10:11]
	v_exp_f32_e32 v14, v0
	v_mul_f32_e32 v0, 0xbfb8aa3b, v13
	v_exp_f32_e32 v15, v0
	v_cvt_pk_bf16_f32 v10, v10, v11
; DI float siluf_(float x) { return x / (1.f + __expf(-x)); }
; DI void st_bf4(bf16_t* dst, f32x4 v) { u32x2 o; o.x = pk2(v[0], v[1]); o.y = pk2(v[2], v[3]); *(u32x2*)dst = o; }
; DI void ffn1_item(const Params& p, int l, int item, bf16_t* lds) {
;     ...
;   for (int mi = 0; mi < 4; ++mi)
; #pragma unroll
;     for (int np = 0; np < 4; ++np) {
;       const int t = m0 + (wid >> 1) * 64 + mi * 16 + (lane & 15);
;       const int hcol = (((n0 + (wid & 1) * 128) >> 5) + np) * 16 + (lane >> 4) * 4;
;       f32x4 g = acc[mi][np * 2], u = acc[mi][np * 2 + 1], o;
; #pragma unroll
;       for (int r = 0; r < 4; ++r) o[r] = siluf_(g[r]) * u[r];
;       st_bf4(hid + (size_t)t * FH + hcol, o);
;     }
	v_pk_add_f32 v[14:15], v[14:15], 1.0 op_sel_hi:[1,0]
	s_nop 0
	v_div_scale_f32 v0, s[10:11], v15, v15, v13
	v_rcp_f32_e32 v28, v0
	s_nop 0
	v_fma_f32 v29, -v0, v28, 1.0
	v_fmac_f32_e32 v28, v29, v28
	v_div_scale_f32 v29, vcc, v13, v15, v13
	v_mul_f32_e32 v30, v29, v28
	v_fma_f32 v31, -v0, v30, v29
	v_fmac_f32_e32 v30, v31, v28
	v_fma_f32 v0, -v0, v30, v29
	v_div_fmas_f32 v0, v0, v28, v30
	v_div_fixup_f32 v13, v0, v15, v13
	v_div_scale_f32 v0, s[10:11], v14, v14, v12
	v_rcp_f32_e32 v15, v0
	s_nop 0
	v_fma_f32 v28, -v0, v15, 1.0
	v_fmac_f32_e32 v15, v28, v15
	v_div_scale_f32 v28, vcc, v12, v14, v12
	v_mul_f32_e32 v29, v28, v15
	v_fma_f32 v30, -v0, v29, v28
	v_fmac_f32_e32 v29, v30, v15
	v_fma_f32 v0, -v0, v29, v28
	v_div_fmas_f32 v0, v0, v15, v29
	v_div_fixup_f32 v12, v0, v14, v12
	v_pk_mul_f32 v[12:13], v[16:17], v[12:13]
	v_mul_f32_e32 v0, 0xbfb8aa3b, v18
	v_cvt_pk_bf16_f32 v11, v12, v13
	v_mov_b32_e32 v240, v10
	v_mov_b32_e32 v241, v11
	v_lshl_add_u64 v[246:247], v[26:27], 0, v[248:249]
	s_nop 0
	v_permlane16_swap_b32_e32 v238, v240
	v_permlane16_swap_b32_e32 v239, v241
	global_store_dwordx4 v[246:247], v[238:241], off
	v_exp_f32_e32 v10, v0
	v_mul_f32_e32 v0, 0xbfb8aa3b, v19
	v_exp_f32_e32 v11, v0
	s_nop 0
	v_pk_add_f32 v[10:11], v[10:11], 1.0 op_sel_hi:[1,0]
	s_nop 0
	v_div_scale_f32 v0, s[10:11], v11, v11, v19
	v_rcp_f32_e32 v12, v0
	s_nop 0
	v_fma_f32 v13, -v0, v12, 1.0
	v_fmac_f32_e32 v12, v13, v12
	v_div_scale_f32 v13, vcc, v19, v11, v19
	v_mul_f32_e32 v14, v13, v12
	v_fma_f32 v15, -v0, v14, v13
	v_fmac_f32_e32 v14, v15, v12
	v_fma_f32 v0, -v0, v14, v13
	v_div_fmas_f32 v0, v0, v12, v14
	v_div_fixup_f32 v11, v0, v11, v19
	v_div_scale_f32 v0, s[10:11], v10, v10, v18
	v_rcp_f32_e32 v12, v0
	s_nop 0
	v_fma_f32 v13, -v0, v12, 1.0
	v_fmac_f32_e32 v12, v13, v12
	v_div_scale_f32 v13, vcc, v18, v10, v18
	v_mul_f32_e32 v14, v13, v12
	v_fma_f32 v15, -v0, v14, v13
	v_fmac_f32_e32 v14, v15, v12
	v_fma_f32 v0, -v0, v14, v13
	v_div_fmas_f32 v0, v0, v12, v14
	v_div_fixup_f32 v10, v0, v10, v18
	v_mul_f32_e32 v0, 0xbfb8aa3b, v20
	v_exp_f32_e32 v12, v0
	v_mul_f32_e32 v0, 0xbfb8aa3b, v21
	v_exp_f32_e32 v13, v0
	v_pk_mul_f32 v[10:11], v[22:23], v[10:11]
	v_pk_add_f32 v[12:13], v[12:13], 1.0 op_sel_hi:[1,0]
	s_nop 0
	v_div_scale_f32 v0, s[10:11], v13, v13, v21
	v_rcp_f32_e32 v14, v0
	v_cvt_pk_bf16_f32 v10, v10, v11
	v_fma_f32 v15, -v0, v14, 1.0
	v_fmac_f32_e32 v14, v15, v14
	v_div_scale_f32 v15, vcc, v21, v13, v21
	v_mul_f32_e32 v16, v15, v14
	v_fma_f32 v17, -v0, v16, v15
	v_fmac_f32_e32 v16, v17, v14
	v_fma_f32 v0, -v0, v16, v15
	v_div_fmas_f32 v0, v0, v14, v16
	v_div_fixup_f32 v13, v0, v13, v21
	v_div_scale_f32 v0, s[10:11], v12, v12, v20
	v_rcp_f32_e32 v14, v0
	s_nop 0
	v_fma_f32 v15, -v0, v14, 1.0
	v_fmac_f32_e32 v14, v15, v14
	v_div_scale_f32 v15, vcc, v20, v12, v20
	v_mul_f32_e32 v16, v15, v14
	v_fma_f32 v17, -v0, v16, v15
	v_fmac_f32_e32 v16, v17, v14
	v_fma_f32 v0, -v0, v16, v15
	v_div_fmas_f32 v0, v0, v14, v16
	v_div_fixup_f32 v12, v0, v12, v20
	v_pk_mul_f32 v[12:13], v[24:25], v[12:13]
	v_mul_f32_e32 v0, 0xbfb8aa3b, v6
	v_cvt_pk_bf16_f32 v11, v12, v13
	v_mov_b32_e32 v242, v10
	v_mov_b32_e32 v243, v11
	v_exp_f32_e32 v10, v0
	v_mul_f32_e32 v0, 0xbfb8aa3b, v7
	v_exp_f32_e32 v11, v0
	s_nop 0
	v_pk_add_f32 v[10:11], v[10:11], 1.0 op_sel_hi:[1,0]
	s_nop 0
	v_div_scale_f32 v0, s[10:11], v11, v11, v7
	v_rcp_f32_e32 v12, v0
	s_nop 0
	v_fma_f32 v13, -v0, v12, 1.0
	v_fmac_f32_e32 v12, v13, v12
	v_div_scale_f32 v13, vcc, v7, v11, v7
	v_mul_f32_e32 v14, v13, v12
	v_fma_f32 v15, -v0, v14, v13
	v_fmac_f32_e32 v14, v15, v12
	v_fma_f32 v0, -v0, v14, v13
	v_div_fmas_f32 v0, v0, v12, v14
	v_div_fixup_f32 v7, v0, v11, v7
	v_div_scale_f32 v0, s[10:11], v10, v10, v6
	v_rcp_f32_e32 v11, v0
	s_nop 0
	v_fma_f32 v12, -v0, v11, 1.0
	v_fmac_f32_e32 v11, v12, v11
	v_div_scale_f32 v12, vcc, v6, v10, v6
	v_mul_f32_e32 v13, v12, v11
	v_fma_f32 v14, -v0, v13, v12
	v_fmac_f32_e32 v13, v14, v11
	v_fma_f32 v0, -v0, v13, v12
	v_div_fmas_f32 v0, v0, v11, v13
	v_div_fixup_f32 v6, v0, v10, v6
	v_mul_f32_e32 v0, 0xbfb8aa3b, v8
	v_pk_mul_f32 v[2:3], v[2:3], v[6:7]
	v_exp_f32_e32 v6, v0
	v_mul_f32_e32 v0, 0xbfb8aa3b, v9
	v_exp_f32_e32 v7, v0
	v_cvt_pk_bf16_f32 v2, v2, v3
	v_pk_add_f32 v[6:7], v[6:7], 1.0 op_sel_hi:[1,0]
	s_nop 0
	v_div_scale_f32 v0, s[10:11], v7, v7, v9
	v_rcp_f32_e32 v10, v0
	s_nop 0
	v_fma_f32 v11, -v0, v10, 1.0
	v_fmac_f32_e32 v10, v11, v10
	v_div_scale_f32 v11, vcc, v9, v7, v9
	v_mul_f32_e32 v12, v11, v10
	v_fma_f32 v13, -v0, v12, v11
	v_fmac_f32_e32 v12, v13, v10
	v_fma_f32 v0, -v0, v12, v11
	v_div_fmas_f32 v0, v0, v10, v12
	v_div_fixup_f32 v7, v0, v7, v9
	v_div_scale_f32 v0, s[10:11], v6, v6, v8
	v_rcp_f32_e32 v9, v0
	s_nop 0
	v_fma_f32 v10, -v0, v9, 1.0
	v_fmac_f32_e32 v9, v10, v9
	v_div_scale_f32 v10, vcc, v8, v6, v8
	v_mul_f32_e32 v11, v10, v9
	v_fma_f32 v12, -v0, v11, v10
	v_fmac_f32_e32 v11, v12, v9
	v_fma_f32 v0, -v0, v11, v10
	v_div_fmas_f32 v0, v0, v9, v11
	v_div_fixup_f32 v6, v0, v6, v8
	v_pk_mul_f32 v[4:5], v[4:5], v[6:7]
	s_nop 0
	v_cvt_pk_bf16_f32 v3, v4, v5
	v_mov_b32_e32 v244, v2
	v_mov_b32_e32 v245, v3
	v_lshl_add_u64 v[246:247], v[26:27], 0, v[248:249]
	s_nop 0
	v_permlane16_swap_b32_e32 v242, v244
	v_permlane16_swap_b32_e32 v243, v245
	global_store_dwordx4 v[246:247], v[242:245], off offset:64
	s_cbranch_scc0 .LBB0_107
	v_not_b32_e32 v172, 31
	v_mov_b32_e32 v173, v232
	v_mov_b32_e32 v174, v237

; DI unsigned pk2(float lo, float hi) { f32x2_t v; v[0] = lo; v[1] = hi; bf16x2_t b = __builtin_convertvector(v, bf16x2_t); return __builtin_bit_cast(unsigned, b); }
; DI void st_bf4(bf16_t* dst, f32x4 v) { u32x2 o; o.x = pk2(v[0], v[1]); o.y = pk2(v[2], v[3]); *(u32x2*)dst = o; }
; DI void inproj_item(const Params& p, int l, int item, bf16_t* lds) {
;     ...
;     EPI_LOOP({
;       st_bf4(dst + (size_t)t * ld + cb + cl, v);
;       if (nt == 28) { int nn = n0 + cl; if (nn >= 7328 && nn < 7336) *(f32x4*)(BA + (size_t)t * 8 + (nn - 7328)) = v; }
;     })
.LBB0_973:
	v_and_b32_e32 v150, 16, v227
	v_lshrrev_b32_e32 v151, 1, v150
	v_add_u32_e32 v150, v150, v151
	v_mov_b32_e32 v151, 0
	v_mov_b32_e32 v0, v201
	v_mov_b32_e32 v131, v201
	s_movk_i32 s10, 0x80
	v_ashrrev_i32_e32 v130, 1, v131
	v_and_b32_e32 v130, 0xffffffc0, v130
	v_add_u32_e32 v130, s36, v130
	v_and_or_b32 v130, v0, 15, v130
	v_lshrrev_b32_e32 v0, 2, v0
	v_lshlrev_b32_e32 v131, 1, v131
	v_and_b32_e32 v0, 12, v0
	s_ashr_i32 s31, s30, 31
	v_and_or_b32 v136, v131, s10, v0
	s_lshl_b64 s[10:11], s[30:31], 1
	v_ashrrev_i32_e32 v131, 31, v130
	s_add_u32 s40, s42, s10
	v_mul_lo_u32 v0, s38, v131
	v_mul_lo_u32 v134, s39, v130
	v_mad_u64_u32 v[132:133], s[12:13], s38, v130, 0
	s_addc_u32 s41, s43, s11
	v_add3_u32 v133, v133, v0, v134
	v_lshl_add_u64 v[132:133], v[132:133], 1, s[40:41]
	v_lshlrev_b32_e32 v0, 1, v136
	v_lshl_add_u64 v[134:135], v[132:133], 0, v[0:1]
	v_cvt_pk_bf16_f32 v140, v110, v111
	v_cvt_pk_bf16_f32 v141, v112, v113
	v_cvt_pk_bf16_f32 v142, v106, v107
	v_cvt_pk_bf16_f32 v143, v108, v109
	v_lshl_add_u64 v[148:149], v[134:135], 0, v[150:151]
	s_nop 0
	v_permlane16_swap_b32_e32 v140, v142
	v_permlane16_swap_b32_e32 v141, v143
	global_store_dwordx4 v[148:149], v[140:143], off
	s_movk_i32 s12, 0xa8
	s_cmp_eq_u32 s9, 28
	v_bitop3_b32 v132, v136, s12, 32 bitop3:0xc8
	s_movk_i32 s12, 0xa0
	s_cselect_b64 s[10:11], -1, 0
	v_cmp_eq_u32_e32 vcc, s12, v132
	s_and_b64 s[44:45], s[10:11], vcc
	v_lshlrev_b32_e32 v132, 2, v136
	s_and_saveexec_b64 s[46:47], s[44:45]
	s_cbranch_execz .LBB0_975
	v_lshlrev_b64 v[136:137], 5, v[130:131]
	v_lshl_add_u64 v[136:137], s[94:95], 0, v[136:137]
	v_mov_b32_e32 v133, v1
	v_lshl_add_u64 v[136:137], v[136:137], 0, v[132:133]
	v_add_co_u32_e32 v136, vcc, 0x153ff000, v136
	s_nop 1
	v_addc_co_u32_e32 v137, vcc, 0, v137, vcc
	global_store_dwordx4 v[136:137], v[102:105], off offset:3584
.LBB0_975:
	s_or_b64 exec, exec, s[46:47]
	v_cvt_pk_bf16_f32 v144, v102, v103
	v_cvt_pk_bf16_f32 v145, v104, v105
	v_cvt_pk_bf16_f32 v146, v98, v99
	v_cvt_pk_bf16_f32 v147, v100, v101
	v_lshl_add_u64 v[148:149], v[134:135], 0, v[150:151]
	s_nop 0
	v_permlane16_swap_b32_e32 v144, v146
	v_permlane16_swap_b32_e32 v145, v147
	global_store_dwordx4 v[148:149], v[144:147], off offset:64
	v_cvt_pk_bf16_f32 v140, v126, v127
	v_cvt_pk_bf16_f32 v141, v128, v129
	v_cvt_pk_bf16_f32 v142, v122, v123
	v_cvt_pk_bf16_f32 v143, v124, v125
	v_lshl_add_u64 v[148:149], v[134:135], 0, v[150:151]
	s_nop 0
	v_permlane16_swap_b32_e32 v140, v142
	v_permlane16_swap_b32_e32 v141, v143
	global_store_dwordx4 v[148:149], v[140:143], off offset:128
	v_cvt_pk_bf16_f32 v144, v118, v119
	v_cvt_pk_bf16_f32 v145, v120, v121
	v_cvt_pk_bf16_f32 v146, v114, v115
	v_cvt_pk_bf16_f32 v147, v116, v117
	v_lshl_add_u64 v[148:149], v[134:135], 0, v[150:151]
	s_nop 0
	v_permlane16_swap_b32_e32 v144, v146
	v_permlane16_swap_b32_e32 v145, v147
	global_store_dwordx4 v[148:149], v[144:147], off offset:192
	v_or_b32_e32 v136, 16, v130
	v_ashrrev_i32_e32 v137, 31, v136
	v_mul_lo_u32 v131, s38, v137
	v_mul_lo_u32 v133, s39, v136
	v_mad_u64_u32 v[134:135], s[10:11], s38, v136, 0
	v_add3_u32 v135, v135, v131, v133
	v_lshl_add_u64 v[134:135], v[134:135], 1, s[40:41]
	v_lshl_add_u64 v[134:135], v[134:135], 0, v[0:1]
	v_cvt_pk_bf16_f32 v140, v78, v79
	v_cvt_pk_bf16_f32 v141, v80, v81
	v_cvt_pk_bf16_f32 v142, v74, v75
	v_cvt_pk_bf16_f32 v143, v76, v77
	v_lshl_add_u64 v[148:149], v[134:135], 0, v[150:151]
	s_nop 0
	v_permlane16_swap_b32_e32 v140, v142
	v_permlane16_swap_b32_e32 v141, v143
	global_store_dwordx4 v[148:149], v[140:143], off
	s_and_saveexec_b64 s[46:47], s[44:45]
	s_cbranch_execz .LBB0_977
	v_lshlrev_b64 v[136:137], 5, v[136:137]
	v_lshl_add_u64 v[136:137], s[94:95], 0, v[136:137]
	v_mov_b32_e32 v133, v1
	v_lshl_add_u64 v[136:137], v[136:137], 0, v[132:133]
	v_add_co_u32_e32 v136, vcc, 0x153ff000, v136
	s_nop 1
	v_addc_co_u32_e32 v137, vcc, 0, v137, vcc
	global_store_dwordx4 v[136:137], v[70:73], off offset:3584
; DI unsigned pk2(float lo, float hi) { f32x2_t v; v[0] = lo; v[1] = hi; bf16x2_t b = __builtin_convertvector(v, bf16x2_t); return __builtin_bit_cast(unsigned, b); }
; DI void st_bf4(bf16_t* dst, f32x4 v) { u32x2 o; o.x = pk2(v[0], v[1]); o.y = pk2(v[2], v[3]); *(u32x2*)dst = o; }
; DI void inproj_item(const Params& p, int l, int item, bf16_t* lds) {
;     ...
;     EPI_LOOP({
;       st_bf4(dst + (size_t)t * ld + cb + cl, v);
;       if (nt == 28) { int nn = n0 + cl; if (nn >= 7328 && nn < 7336) *(f32x4*)(BA + (size_t)t * 8 + (nn - 7328)) = v; }
;     })
.LBB0_977:
	s_or_b64 exec, exec, s[46:47]
	v_cvt_pk_bf16_f32 v144, v70, v71
	v_cvt_pk_bf16_f32 v145, v72, v73
	v_cvt_pk_bf16_f32 v146, v66, v67
	v_cvt_pk_bf16_f32 v147, v68, v69
	v_lshl_add_u64 v[148:149], v[134:135], 0, v[150:151]
	s_nop 0
	v_permlane16_swap_b32_e32 v144, v146
	v_permlane16_swap_b32_e32 v145, v147
	global_store_dwordx4 v[148:149], v[144:147], off offset:64
	v_cvt_pk_bf16_f32 v140, v94, v95
	v_cvt_pk_bf16_f32 v141, v96, v97
	v_cvt_pk_bf16_f32 v142, v90, v91
	v_cvt_pk_bf16_f32 v143, v92, v93
	v_lshl_add_u64 v[148:149], v[134:135], 0, v[150:151]
	s_nop 0
	v_permlane16_swap_b32_e32 v140, v142
	v_permlane16_swap_b32_e32 v141, v143
	global_store_dwordx4 v[148:149], v[140:143], off offset:128
	v_cvt_pk_bf16_f32 v144, v86, v87
	v_cvt_pk_bf16_f32 v145, v88, v89
	v_cvt_pk_bf16_f32 v146, v82, v83
	v_cvt_pk_bf16_f32 v147, v84, v85
	v_lshl_add_u64 v[148:149], v[134:135], 0, v[150:151]
	s_nop 0
	v_permlane16_swap_b32_e32 v144, v146
	v_permlane16_swap_b32_e32 v145, v147
	global_store_dwordx4 v[148:149], v[144:147], off offset:192
	v_or_b32_e32 v136, 32, v130
	v_ashrrev_i32_e32 v137, 31, v136
	v_mul_lo_u32 v131, s38, v137
	v_mul_lo_u32 v133, s39, v136
	v_mad_u64_u32 v[134:135], s[10:11], s38, v136, 0
	v_add3_u32 v135, v135, v131, v133
	v_lshl_add_u64 v[134:135], v[134:135], 1, s[40:41]
	v_lshl_add_u64 v[134:135], v[134:135], 0, v[0:1]
	v_cvt_pk_bf16_f32 v140, v46, v47
	v_cvt_pk_bf16_f32 v141, v48, v49
	v_cvt_pk_bf16_f32 v142, v42, v43
	v_cvt_pk_bf16_f32 v143, v44, v45
	v_lshl_add_u64 v[148:149], v[134:135], 0, v[150:151]
	s_nop 0
	v_permlane16_swap_b32_e32 v140, v142
	v_permlane16_swap_b32_e32 v141, v143
	global_store_dwordx4 v[148:149], v[140:143], off
	s_and_saveexec_b64 s[46:47], s[44:45]
	s_cbranch_execz .LBB0_979
	v_lshlrev_b64 v[136:137], 5, v[136:137]
	v_lshl_add_u64 v[136:137], s[94:95], 0, v[136:137]
	v_mov_b32_e32 v133, v1
	v_lshl_add_u64 v[136:137], v[136:137], 0, v[132:133]
	v_add_co_u32_e32 v136, vcc, 0x153ff000, v136
	s_nop 1
	v_addc_co_u32_e32 v137, vcc, 0, v137, vcc
	global_store_dwordx4 v[136:137], v[38:41], off offset:3584
.LBB0_979:
	s_or_b64 exec, exec, s[46:47]
	v_cvt_pk_bf16_f32 v144, v38, v39
	v_cvt_pk_bf16_f32 v145, v40, v41
	v_cvt_pk_bf16_f32 v146, v34, v35
	v_cvt_pk_bf16_f32 v147, v36, v37
	v_lshl_add_u64 v[148:149], v[134:135], 0, v[150:151]
	s_nop 0
	v_permlane16_swap_b32_e32 v144, v146
	v_permlane16_swap_b32_e32 v145, v147
	global_store_dwordx4 v[148:149], v[144:147], off offset:64
	v_cvt_pk_bf16_f32 v140, v62, v63
	v_cvt_pk_bf16_f32 v141, v64, v65
	v_cvt_pk_bf16_f32 v142, v58, v59
	v_cvt_pk_bf16_f32 v143, v60, v61
	v_lshl_add_u64 v[148:149], v[134:135], 0, v[150:151]
	s_nop 0
	v_permlane16_swap_b32_e32 v140, v142
	v_permlane16_swap_b32_e32 v141, v143
	global_store_dwordx4 v[148:149], v[140:143], off offset:128
	v_cvt_pk_bf16_f32 v144, v54, v55
	v_cvt_pk_bf16_f32 v145, v56, v57
	v_cvt_pk_bf16_f32 v146, v50, v51
	v_cvt_pk_bf16_f32 v147, v52, v53
	v_lshl_add_u64 v[148:149], v[134:135], 0, v[150:151]
	s_nop 0
	v_permlane16_swap_b32_e32 v144, v146
	v_permlane16_swap_b32_e32 v145, v147
	global_store_dwordx4 v[148:149], v[144:147], off offset:192
	v_or_b32_e32 v134, 48, v130
	v_ashrrev_i32_e32 v135, 31, v134
	v_mul_lo_u32 v133, s38, v135
	v_mul_lo_u32 v136, s39, v134
	v_mad_u64_u32 v[130:131], s[10:11], s38, v134, 0
	v_add3_u32 v131, v131, v133, v136
	v_lshl_add_u64 v[130:131], v[130:131], 1, s[40:41]
	v_lshl_add_u64 v[130:131], v[130:131], 0, v[0:1]
	v_cvt_pk_bf16_f32 v140, v14, v15
	v_cvt_pk_bf16_f32 v141, v16, v17
	v_cvt_pk_bf16_f32 v142, v10, v11
	v_cvt_pk_bf16_f32 v143, v12, v13
	v_lshl_add_u64 v[148:149], v[130:131], 0, v[150:151]
	s_nop 0
	v_permlane16_swap_b32_e32 v140, v142
	v_permlane16_swap_b32_e32 v141, v143
	global_store_dwordx4 v[148:149], v[140:143], off
	s_and_saveexec_b64 s[40:41], s[44:45]
	s_cbranch_execz .LBB0_981
	v_lshlrev_b64 v[134:135], 5, v[134:135]
	v_lshl_add_u64 v[134:135], s[94:95], 0, v[134:135]
	v_mov_b32_e32 v133, v1
	v_lshl_add_u64 v[132:133], v[134:135], 0, v[132:133]
	v_add_co_u32_e32 v132, vcc, 0x153ff000, v132
	s_nop 1
	v_addc_co_u32_e32 v133, vcc, 0, v133, vcc
	global_store_dwordx4 v[132:133], v[6:9], off offset:3584
.LBB0_981:
	s_or_b64 exec, exec, s[40:41]
	v_cvt_pk_bf16_f32 v144, v6, v7
	v_cvt_pk_bf16_f32 v145, v8, v9
	v_cvt_pk_bf16_f32 v146, v2, v3
	v_cvt_pk_bf16_f32 v147, v4, v5
	v_lshl_add_u64 v[148:149], v[130:131], 0, v[150:151]
	s_nop 0
	v_permlane16_swap_b32_e32 v144, v146
	v_permlane16_swap_b32_e32 v145, v147
	global_store_dwordx4 v[148:149], v[144:147], off offset:64
	v_cvt_pk_bf16_f32 v140, v30, v31
	v_cvt_pk_bf16_f32 v141, v32, v33
	v_cvt_pk_bf16_f32 v142, v26, v27
	v_cvt_pk_bf16_f32 v143, v28, v29
	v_lshl_add_u64 v[148:149], v[130:131], 0, v[150:151]
	s_nop 0
	v_permlane16_swap_b32_e32 v140, v142
	v_permlane16_swap_b32_e32 v141, v143
	global_store_dwordx4 v[148:149], v[140:143], off offset:128
	s_mov_b64 s[40:41], 0
	v_cvt_pk_bf16_f32 v144, v22, v23
	v_cvt_pk_bf16_f32 v145, v24, v25
	v_cvt_pk_bf16_f32 v146, v18, v19
	v_cvt_pk_bf16_f32 v147, v20, v21
	v_lshl_add_u64 v[148:149], v[130:131], 0, v[150:151]
	s_nop 0
	v_permlane16_swap_b32_e32 v144, v146
	v_permlane16_swap_b32_e32 v145, v147
	global_store_dwordx4 v[148:149], v[144:147], off offset:192
